# QKV rope epilogue: second-half cos/sin loads requested with the first half's; in-proj second-half hoist, R peeled-iteration trim, attention gamma hoist
# baseline (speedup 1.0000x reference)
.LBB0_202:
	s_add_i32 s24, s92, s53
	s_and_b32 s14, s24, -4
	s_cmp_lg_u32 s14, 4
	s_cselect_b64 s[14:15], -1, 0
	v_add_u32_e32 v186, s62, v194
	s_and_b64 s[14:15], s[36:37], s[14:15]
	s_and_b64 s[22:23], s[14:15], s[4:5]
	v_lshlrev_b32_e32 v181, 3, v186
	v_mov_b32_e32 v164, 1.0
	v_mov_b32_e32 v165, 1.0
	v_mov_b32_e32 v166, 1.0
	v_mov_b32_e32 v167, 1.0
	v_mov_b32_e32 v168, 1.0
	v_mov_b32_e32 v169, 1.0
	v_mov_b32_e32 v170, 1.0
	v_mov_b32_e32 v171, 1.0
	v_mov_b32_e32 v172, 1.0
	v_mov_b32_e32 v173, 1.0
	v_mov_b32_e32 v174, 1.0
	v_mov_b32_e32 v175, 1.0
	v_mov_b32_e32 v160, 1.0
	v_mov_b32_e32 v161, 1.0
	v_mov_b32_e32 v162, 1.0
	v_mov_b32_e32 v163, 1.0
	v_mov_b32_e32 v0, 0
	v_mov_b32_e32 v1, 0
	v_mov_b32_e32 v2, 0
	v_mov_b32_e32 v3, 0
	v_mov_b32_e32 v4, 0
	v_mov_b32_e32 v5, 0
	v_mov_b32_e32 v6, 0
	v_mov_b32_e32 v7, 0
	v_mov_b32_e32 v8, 0
	v_mov_b32_e32 v9, 0
	v_mov_b32_e32 v10, 0
	v_mov_b32_e32 v11, 0
	v_mov_b32_e32 v12, 0
	v_mov_b32_e32 v13, 0
	v_mov_b32_e32 v14, 0
	v_mov_b32_e32 v15, 0
	s_and_saveexec_b64 s[14:15], s[22:23]
	s_cbranch_execz .Lrope0_skip
	v_mov_b32_e32 v17, v213
	v_and_b32_e32 v16, 0xfff8, v181
	v_lshlrev_b32_e32 v16, 2, v16
	v_lshl_add_u64 v[18:19], v[182:183], 0, v[16:17]
	v_lshl_add_u64 v[20:21], v[184:185], 0, v[16:17]
	global_load_dwordx4 v[164:167], v[18:19], off
	global_load_dwordx4 v[0:3], v[20:21], off
	v_add_u32_e32 v16, 0x80, v181
	v_and_b32_e32 v16, 0xfff8, v16
	v_lshlrev_b32_e32 v16, 2, v16
	v_lshl_add_u64 v[18:19], v[182:183], 0, v[16:17]
	v_lshl_add_u64 v[20:21], v[184:185], 0, v[16:17]
	global_load_dwordx4 v[168:171], v[18:19], off
	global_load_dwordx4 v[4:7], v[20:21], off
	v_add_u32_e32 v16, 0x100, v181
	v_and_b32_e32 v16, 0xfff8, v16
	v_lshlrev_b32_e32 v16, 2, v16
	v_lshl_add_u64 v[18:19], v[182:183], 0, v[16:17]
	v_lshl_add_u64 v[20:21], v[184:185], 0, v[16:17]
	global_load_dwordx4 v[172:175], v[18:19], off
	global_load_dwordx4 v[8:11], v[20:21], off
	v_add_u32_e32 v16, 0x180, v181
	v_and_b32_e32 v16, 0xfff8, v16
	v_lshlrev_b32_e32 v16, 2, v16
	v_lshl_add_u64 v[18:19], v[182:183], 0, v[16:17]
	v_lshl_add_u64 v[20:21], v[184:185], 0, v[16:17]
	global_load_dwordx4 v[160:163], v[18:19], off
	global_load_dwordx4 v[12:15], v[20:21], off
	v_add_u32_e32 v16, 0x400, v181
	v_and_b32_e32 v16, 0xfff8, v16
	v_lshlrev_b32_e32 v16, 2, v16
	v_lshl_add_u64 v[18:19], v[182:183], 0, v[16:17]
	v_lshl_add_u64 v[20:21], v[184:185], 0, v[16:17]
	global_load_dwordx4 v[200:203], v[18:19], off
	global_load_dwordx4 v[204:207], v[20:21], off
	v_add_u32_e32 v16, 0x480, v181
	v_and_b32_e32 v16, 0xfff8, v16
	v_lshlrev_b32_e32 v16, 2, v16
	v_lshl_add_u64 v[18:19], v[182:183], 0, v[16:17]
	v_lshl_add_u64 v[20:21], v[184:185], 0, v[16:17]
	global_load_dwordx4 v[208:211], v[18:19], off
	global_load_dwordx4 v[216:219], v[20:21], off
	v_add_u32_e32 v16, 0x500, v181
	v_and_b32_e32 v16, 0xfff8, v16
	v_lshlrev_b32_e32 v16, 2, v16
	v_lshl_add_u64 v[18:19], v[182:183], 0, v[16:17]
	v_lshl_add_u64 v[20:21], v[184:185], 0, v[16:17]
	global_load_dwordx4 v[220:223], v[18:19], off
	global_load_dwordx4 v[224:227], v[20:21], off
	v_add_u32_e32 v16, 0x580, v181
	v_and_b32_e32 v16, 0xfff8, v16
	v_lshlrev_b32_e32 v16, 2, v16
	v_lshl_add_u64 v[18:19], v[182:183], 0, v[16:17]
	v_lshl_add_u64 v[20:21], v[184:185], 0, v[16:17]
	global_load_dwordx4 v[240:243], v[18:19], off
	global_load_dwordx4 v[244:247], v[20:21], off
.Lrope0_skip:
	s_or_b64 exec, exec, s[14:15]
	s_waitcnt vmcnt(0)
	s_cmp_lt_i32 s24, 8
	s_mov_b32 s14, 0x26000000
	s_cselect_b32 s14, s14, 0x29000000
	s_cmp_gt_i32 s24, 7
	s_cselect_b64 vcc, -1, 0
	s_cmp_gt_i32 s24, 3
	s_cselect_b32 s14, s14, 0x24000000
	s_lshl_b32 s14, s14, 1
	v_mov_b32_e32 v17, 0x3e38aa3b
	s_add_u32 s14, s30, s14
	v_cndmask_b32_e32 v188, 1.0, v17, vcc
	s_addc_u32 s15, s31, 0
	s_lshl_b32 s24, s92, 8
	s_and_b32 s24, s24, 0x300
	v_pk_mul_f32 v[24:25], v[188:189], v[2:3] op_sel_hi:[0,1]
	v_pk_mul_f32 v[26:27], v[188:189], v[0:1] op_sel_hi:[0,1]
	v_or_b32_e32 v17, s24, v196
	v_pk_mul_f32 v[20:21], v[188:189], v[166:167] op_sel_hi:[0,1]
	v_pk_mul_f32 v[22:23], v[188:189], v[164:165] op_sel_hi:[0,1]
	v_pk_mul_f32 v[0:1], v[154:155], v[24:25]
	v_pk_mul_f32 v[2:3], v[152:153], v[26:27]
	v_lshlrev_b32_e32 v18, 1, v17
	v_mov_b32_e32 v19, v213
	v_ashrrev_i32_e32 v187, 31, v186
	v_pk_fma_f32 v[28:29], v[158:159], v[20:21], v[0:1] neg_lo:[0,0,1] neg_hi:[0,0,1]
	v_pk_fma_f32 v[0:1], v[156:157], v[22:23], v[2:3] neg_lo:[0,0,1] neg_hi:[0,0,1]
	v_pk_mul_f32 v[2:3], v[154:155], v[20:21]
	v_pk_mul_f32 v[30:31], v[152:153], v[22:23]
	v_lshl_add_u64 v[190:191], s[14:15], 0, v[18:19]
	v_lshlrev_b64 v[18:19], 11, v[186:187]
	v_pk_fma_f32 v[152:153], v[158:159], v[24:25], v[2:3]
	v_pk_fma_f32 v[2:3], v[156:157], v[26:27], v[30:31]
	v_lshl_add_u64 v[18:19], v[190:191], 0, v[18:19]
	v_cvt_pk_bf16_f32 v0, v0, v1
	v_cvt_pk_bf16_f32 v1, v28, v29
	v_cvt_pk_bf16_f32 v2, v2, v3
	v_cvt_pk_bf16_f32 v3, v152, v153
	global_store_dwordx4 v[18:19], v[0:3], off
	v_pk_mul_f32 v[6:7], v[188:189], v[6:7] op_sel_hi:[0,1]
	v_pk_mul_f32 v[4:5], v[188:189], v[4:5] op_sel_hi:[0,1]
	v_pk_mul_f32 v[0:1], v[146:147], v[24:25]
	v_pk_mul_f32 v[2:3], v[144:145], v[26:27]
	v_pk_fma_f32 v[28:29], v[150:151], v[20:21], v[0:1] neg_lo:[0,0,1] neg_hi:[0,0,1]
	v_pk_fma_f32 v[0:1], v[148:149], v[22:23], v[2:3] neg_lo:[0,0,1] neg_hi:[0,0,1]
	v_pk_mul_f32 v[2:3], v[146:147], v[20:21]
	v_pk_mul_f32 v[20:21], v[144:145], v[22:23]
	v_pk_fma_f32 v[22:23], v[150:151], v[24:25], v[2:3]
	v_pk_fma_f32 v[2:3], v[148:149], v[26:27], v[20:21]
	v_cvt_pk_bf16_f32 v0, v0, v1
	v_cvt_pk_bf16_f32 v1, v28, v29
	v_cvt_pk_bf16_f32 v2, v2, v3
	v_cvt_pk_bf16_f32 v3, v22, v23
	s_waitcnt vmcnt(1)
	v_pk_mul_f32 v[22:23], v[188:189], v[168:169] op_sel_hi:[0,1]
	global_store_dwordx4 v[18:19], v[0:3], off offset:256
	v_pk_mul_f32 v[24:25], v[188:189], v[170:171] op_sel_hi:[0,1]
	v_pk_mul_f32 v[26:27], v[136:137], v[22:23]
	v_pk_mul_f32 v[0:1], v[136:137], v[4:5]
	v_pk_mul_f32 v[2:3], v[138:139], v[6:7]
	v_pk_fma_f32 v[0:1], v[140:141], v[22:23], v[0:1] neg_lo:[0,0,1] neg_hi:[0,0,1]
	v_pk_fma_f32 v[2:3], v[142:143], v[24:25], v[2:3] neg_lo:[0,0,1] neg_hi:[0,0,1]
	v_pk_mul_f32 v[28:29], v[138:139], v[24:25]
	v_pk_fma_f32 v[26:27], v[140:141], v[4:5], v[26:27]
	v_pk_fma_f32 v[28:29], v[142:143], v[6:7], v[28:29]
	v_cvt_pk_bf16_f32 v0, v0, v1
	v_cvt_pk_bf16_f32 v1, v2, v3
	v_cvt_pk_bf16_f32 v2, v26, v27
	v_add_co_u32_e32 v26, vcc, s72, v18
	v_cvt_pk_bf16_f32 v3, v28, v29
	s_nop 0
	v_addc_co_u32_e32 v27, vcc, 0, v19, vcc
	global_store_dwordx4 v[26:27], v[0:3], off
	s_mov_b64 s[14:15], 0x8000
	v_lshl_add_u64 v[20:21], v[18:19], 0, s[14:15]
	v_pk_mul_f32 v[0:1], v[128:129], v[4:5]
	v_pk_mul_f32 v[2:3], v[130:131], v[6:7]
	v_pk_fma_f32 v[0:1], v[132:133], v[22:23], v[0:1] neg_lo:[0,0,1] neg_hi:[0,0,1]
	v_pk_fma_f32 v[2:3], v[134:135], v[24:25], v[2:3] neg_lo:[0,0,1] neg_hi:[0,0,1]
	v_pk_mul_f32 v[22:23], v[128:129], v[22:23]
	v_pk_mul_f32 v[24:25], v[130:131], v[24:25]
	v_pk_fma_f32 v[4:5], v[132:133], v[4:5], v[22:23]
	v_pk_fma_f32 v[6:7], v[134:135], v[6:7], v[24:25]
	v_cvt_pk_bf16_f32 v0, v0, v1
	v_cvt_pk_bf16_f32 v1, v2, v3
	v_cvt_pk_bf16_f32 v2, v4, v5
	v_cvt_pk_bf16_f32 v3, v6, v7
	v_pk_mul_f32 v[6:7], v[188:189], v[172:173] op_sel_hi:[0,1]
	v_pk_mul_f32 v[10:11], v[188:189], v[10:11] op_sel_hi:[0,1]
	v_pk_mul_f32 v[8:9], v[188:189], v[8:9] op_sel_hi:[0,1]
	global_store_dwordx4 v[20:21], v[0:3], off offset:256
	v_pk_mul_f32 v[20:21], v[188:189], v[174:175] op_sel_hi:[0,1]
	v_pk_mul_f32 v[22:23], v[120:121], v[6:7]
	v_pk_mul_f32 v[0:1], v[120:121], v[8:9]
	v_pk_mul_f32 v[2:3], v[122:123], v[10:11]
	v_pk_fma_f32 v[0:1], v[124:125], v[6:7], v[0:1] neg_lo:[0,0,1] neg_hi:[0,0,1]
	v_pk_fma_f32 v[2:3], v[126:127], v[20:21], v[2:3] neg_lo:[0,0,1] neg_hi:[0,0,1]
	v_pk_mul_f32 v[24:25], v[122:123], v[20:21]
	v_pk_fma_f32 v[22:23], v[124:125], v[8:9], v[22:23]
	v_pk_fma_f32 v[24:25], v[126:127], v[10:11], v[24:25]
	v_cvt_pk_bf16_f32 v0, v0, v1
	v_cvt_pk_bf16_f32 v1, v2, v3
	v_cvt_pk_bf16_f32 v2, v22, v23
	v_add_co_u32_e32 v22, vcc, s89, v18
	v_cvt_pk_bf16_f32 v3, v24, v25
	s_nop 0
	v_addc_co_u32_e32 v23, vcc, 0, v19, vcc
	global_store_dwordx4 v[22:23], v[0:3], off
	s_mov_b64 s[14:15], 0x10000
	v_lshl_add_u64 v[4:5], v[18:19], 0, s[14:15]
	v_pk_mul_f32 v[0:1], v[112:113], v[8:9]
	v_pk_mul_f32 v[2:3], v[114:115], v[10:11]
	v_pk_fma_f32 v[0:1], v[116:117], v[6:7], v[0:1] neg_lo:[0,0,1] neg_hi:[0,0,1]
	v_pk_fma_f32 v[2:3], v[118:119], v[20:21], v[2:3] neg_lo:[0,0,1] neg_hi:[0,0,1]
	v_pk_mul_f32 v[6:7], v[112:113], v[6:7]
	v_pk_mul_f32 v[20:21], v[114:115], v[20:21]
	v_pk_fma_f32 v[6:7], v[116:117], v[8:9], v[6:7]
	v_pk_fma_f32 v[10:11], v[118:119], v[10:11], v[20:21]
	v_cvt_pk_bf16_f32 v0, v0, v1
	v_cvt_pk_bf16_f32 v1, v2, v3
	v_cvt_pk_bf16_f32 v2, v6, v7
	v_cvt_pk_bf16_f32 v3, v10, v11
	v_pk_mul_f32 v[6:7], v[188:189], v[160:161] op_sel_hi:[0,1]
	v_pk_mul_f32 v[10:11], v[188:189], v[14:15] op_sel_hi:[0,1]
	v_pk_mul_f32 v[12:13], v[188:189], v[12:13] op_sel_hi:[0,1]
	global_store_dwordx4 v[4:5], v[0:3], off offset:256
	v_pk_mul_f32 v[8:9], v[188:189], v[162:163] op_sel_hi:[0,1]
	v_pk_mul_f32 v[14:15], v[104:105], v[6:7]
	v_pk_mul_f32 v[0:1], v[104:105], v[12:13]
	v_pk_mul_f32 v[2:3], v[106:107], v[10:11]
	v_pk_fma_f32 v[0:1], v[108:109], v[6:7], v[0:1] neg_lo:[0,0,1] neg_hi:[0,0,1]
	v_pk_fma_f32 v[2:3], v[110:111], v[8:9], v[2:3] neg_lo:[0,0,1] neg_hi:[0,0,1]
	v_pk_mul_f32 v[20:21], v[106:107], v[8:9]
	v_pk_fma_f32 v[14:15], v[108:109], v[12:13], v[14:15]
	v_pk_fma_f32 v[20:21], v[110:111], v[10:11], v[20:21]
	v_cvt_pk_bf16_f32 v0, v0, v1
	v_cvt_pk_bf16_f32 v1, v2, v3
	v_cvt_pk_bf16_f32 v2, v14, v15
	v_add_co_u32_e32 v14, vcc, s93, v18
	v_cvt_pk_bf16_f32 v3, v20, v21
	s_nop 0
	v_addc_co_u32_e32 v15, vcc, 0, v19, vcc
	global_store_dwordx4 v[14:15], v[0:3], off
	s_mov_b64 s[14:15], 0x18000
	v_lshl_add_u64 v[4:5], v[18:19], 0, s[14:15]
	v_pk_mul_f32 v[0:1], v[96:97], v[12:13]
	v_pk_mul_f32 v[2:3], v[98:99], v[10:11]
	v_pk_fma_f32 v[0:1], v[100:101], v[6:7], v[0:1] neg_lo:[0,0,1] neg_hi:[0,0,1]
	v_pk_fma_f32 v[2:3], v[102:103], v[8:9], v[2:3] neg_lo:[0,0,1] neg_hi:[0,0,1]
	v_pk_mul_f32 v[6:7], v[96:97], v[6:7]
	v_pk_mul_f32 v[8:9], v[98:99], v[8:9]
	v_pk_fma_f32 v[6:7], v[100:101], v[12:13], v[6:7]
	v_pk_fma_f32 v[8:9], v[102:103], v[10:11], v[8:9]
	v_cvt_pk_bf16_f32 v0, v0, v1
	v_cvt_pk_bf16_f32 v1, v2, v3
	v_cvt_pk_bf16_f32 v2, v6, v7
	v_cvt_pk_bf16_f32 v3, v8, v9
	global_store_dwordx4 v[4:5], v[0:3], off offset:256
	v_mov_b32_e32 v16, 1.0
	v_mov_b32_e32 v8, 0
	v_mov_b32_e32 v24, 0
	v_mov_b32_e32 v25, 0
	v_mov_b32_e32 v26, 0
	v_mov_b32_e32 v27, 0
	v_mov_b32_e32 v28, 1.0
	v_mov_b32_e32 v29, 1.0
	v_mov_b32_e32 v30, 1.0
	v_mov_b32_e32 v31, 1.0
	s_and_saveexec_b64 s[14:15], s[22:23]
	s_cbranch_execz .LBB0_212
	v_mov_b64_e32 v[28:29], v[200:201]
	v_mov_b64_e32 v[30:31], v[202:203]
	v_mov_b64_e32 v[24:25], v[204:205]
	v_mov_b64_e32 v[26:27], v[206:207]
.LBB0_212:
	s_or_b64 exec, exec, s[14:15]
	v_mov_b32_e32 v9, 0
	v_mov_b32_e32 v10, 0
	v_mov_b32_e32 v11, 0
	v_mov_b32_e32 v17, 1.0
	v_mov_b32_e32 v18, 1.0
	v_mov_b32_e32 v19, 1.0
	s_and_saveexec_b64 s[14:15], s[22:23]
	s_cbranch_execz .LBB0_214
	v_mov_b64_e32 v[16:17], v[208:209]
	v_mov_b64_e32 v[18:19], v[210:211]
	v_mov_b64_e32 v[8:9], v[216:217]
	v_mov_b64_e32 v[10:11], v[218:219]
.LBB0_214:
	s_or_b64 exec, exec, s[14:15]
	v_mov_b32_e32 v4, 1.0
	v_mov_b32_e32 v0, 0
	v_mov_b32_e32 v12, 0
	v_mov_b32_e32 v13, 0
	v_mov_b32_e32 v14, 0
	v_mov_b32_e32 v15, 0
	v_mov_b32_e32 v20, 1.0
	v_mov_b32_e32 v21, 1.0
	v_mov_b32_e32 v22, 1.0
	v_mov_b32_e32 v23, 1.0
	s_and_saveexec_b64 s[14:15], s[22:23]
	s_cbranch_execz .LBB0_216
	v_mov_b64_e32 v[20:21], v[220:221]
	v_mov_b64_e32 v[22:23], v[222:223]
	v_mov_b64_e32 v[12:13], v[224:225]
	v_mov_b64_e32 v[14:15], v[226:227]
.LBB0_216:
	s_or_b64 exec, exec, s[14:15]
	v_mov_b32_e32 v1, 0
	v_mov_b32_e32 v2, 0
	v_mov_b32_e32 v3, 0
	v_mov_b32_e32 v5, 1.0
	v_mov_b32_e32 v6, 1.0
	v_mov_b32_e32 v7, 1.0
	s_and_saveexec_b64 s[14:15], s[22:23]
	s_cbranch_execz .LBB0_218
	v_mov_b64_e32 v[4:5], v[240:241]
	v_mov_b64_e32 v[6:7], v[242:243]
	v_mov_b64_e32 v[0:1], v[244:245]
	v_mov_b64_e32 v[2:3], v[246:247]
.LBB0_218:
	s_or_b64 exec, exec, s[14:15]
	v_mov_b32_e32 v189, v188
	v_mov_b32_e32 v100, v188
	v_mov_b32_e32 v101, v188
	v_pk_mul_f32 v[102:103], v[100:101], v[26:27]
	v_pk_mul_f32 v[104:105], v[188:189], v[24:25]
	v_lshlrev_b64 v[96:97], 11, v[186:187]
	v_pk_mul_f32 v[30:31], v[100:101], v[30:31]
	v_pk_mul_f32 v[28:29], v[188:189], v[28:29]
	v_pk_mul_f32 v[24:25], v[90:91], v[102:103]
	v_pk_mul_f32 v[26:27], v[88:89], v[104:105]
	v_lshl_add_u64 v[96:97], v[190:191], 0, v[96:97]
	v_pk_fma_f32 v[106:107], v[94:95], v[30:31], v[24:25] neg_lo:[0,0,1] neg_hi:[0,0,1]
	v_pk_fma_f32 v[24:25], v[92:93], v[28:29], v[26:27] neg_lo:[0,0,1] neg_hi:[0,0,1]
	v_pk_mul_f32 v[26:27], v[90:91], v[30:31]
	v_pk_mul_f32 v[88:89], v[88:89], v[28:29]
	s_mov_b32 s14, 0x40000
	v_pk_fma_f32 v[90:91], v[94:95], v[102:103], v[26:27]
	v_pk_fma_f32 v[26:27], v[92:93], v[104:105], v[88:89]
	v_add_co_u32_e32 v88, vcc, s14, v96
	v_cvt_pk_bf16_f32 v24, v24, v25
	v_cvt_pk_bf16_f32 v25, v106, v107
	v_cvt_pk_bf16_f32 v26, v26, v27
	v_cvt_pk_bf16_f32 v27, v90, v91
	v_addc_co_u32_e32 v89, vcc, 0, v97, vcc
	global_store_dwordx4 v[88:89], v[24:27], off
	v_lshl_add_u64 v[98:99], v[96:97], 0, s[42:43]
	s_mov_b64 s[14:15], 0x48000
	v_pk_mul_f32 v[24:25], v[82:83], v[102:103]
	v_pk_mul_f32 v[26:27], v[80:81], v[104:105]
	v_pk_fma_f32 v[88:89], v[86:87], v[30:31], v[24:25] neg_lo:[0,0,1] neg_hi:[0,0,1]
	v_pk_fma_f32 v[24:25], v[84:85], v[28:29], v[26:27] neg_lo:[0,0,1] neg_hi:[0,0,1]
	v_pk_mul_f32 v[26:27], v[82:83], v[30:31]
	v_pk_mul_f32 v[28:29], v[80:81], v[28:29]
	v_pk_fma_f32 v[30:31], v[86:87], v[102:103], v[26:27]
	v_pk_fma_f32 v[26:27], v[84:85], v[104:105], v[28:29]
	v_cvt_pk_bf16_f32 v24, v24, v25
	v_cvt_pk_bf16_f32 v25, v88, v89
	v_cvt_pk_bf16_f32 v26, v26, v27
	v_cvt_pk_bf16_f32 v27, v30, v31
	global_store_dwordx4 v[98:99], v[24:27], off offset:256
	v_pk_mul_f32 v[28:29], v[188:189], v[8:9]
	v_pk_mul_f32 v[18:19], v[100:101], v[18:19]
	v_pk_mul_f32 v[26:27], v[100:101], v[10:11]
	v_pk_mul_f32 v[16:17], v[188:189], v[16:17]
	v_pk_mul_f32 v[8:9], v[74:75], v[26:27]
	v_pk_mul_f32 v[10:11], v[72:73], v[28:29]
	v_lshl_add_u64 v[24:25], v[96:97], 0, s[14:15]
	v_pk_fma_f32 v[30:31], v[78:79], v[18:19], v[8:9] neg_lo:[0,0,1] neg_hi:[0,0,1]
	v_pk_fma_f32 v[8:9], v[76:77], v[16:17], v[10:11] neg_lo:[0,0,1] neg_hi:[0,0,1]
	v_pk_mul_f32 v[10:11], v[74:75], v[18:19]
	v_pk_mul_f32 v[72:73], v[72:73], v[16:17]
	s_mov_b32 s14, 0x48000
	v_pk_fma_f32 v[74:75], v[78:79], v[26:27], v[10:11]
	v_pk_fma_f32 v[10:11], v[76:77], v[28:29], v[72:73]
	v_cvt_pk_bf16_f32 v8, v8, v9
	v_cvt_pk_bf16_f32 v9, v30, v31
	v_add_co_u32_e32 v30, vcc, s14, v96
	v_cvt_pk_bf16_f32 v10, v10, v11
	v_cvt_pk_bf16_f32 v11, v74, v75
	v_addc_co_u32_e32 v31, vcc, 0, v97, vcc
	global_store_dwordx4 v[30:31], v[8:11], off
	v_pk_mul_f32 v[14:15], v[100:101], v[14:15]
	v_pk_mul_f32 v[12:13], v[188:189], v[12:13]
	v_pk_mul_f32 v[8:9], v[66:67], v[26:27]
	v_pk_mul_f32 v[10:11], v[64:65], v[28:29]
	v_pk_fma_f32 v[30:31], v[70:71], v[18:19], v[8:9] neg_lo:[0,0,1] neg_hi:[0,0,1]
	v_pk_fma_f32 v[8:9], v[68:69], v[16:17], v[10:11] neg_lo:[0,0,1] neg_hi:[0,0,1]
	v_pk_mul_f32 v[10:11], v[66:67], v[18:19]
	v_pk_mul_f32 v[16:17], v[64:65], v[16:17]
	v_pk_fma_f32 v[18:19], v[70:71], v[26:27], v[10:11]
	v_pk_fma_f32 v[10:11], v[68:69], v[28:29], v[16:17]
	v_cvt_pk_bf16_f32 v8, v8, v9
	v_cvt_pk_bf16_f32 v9, v30, v31
	v_cvt_pk_bf16_f32 v10, v10, v11
	v_cvt_pk_bf16_f32 v11, v18, v19
	global_store_dwordx4 v[24:25], v[8:11], off offset:256
	s_mov_b64 s[14:15], 0x50000
	v_pk_mul_f32 v[18:19], v[100:101], v[22:23]
	v_pk_mul_f32 v[20:21], v[188:189], v[20:21]
	v_pk_mul_f32 v[8:9], v[58:59], v[14:15]
	v_pk_mul_f32 v[10:11], v[56:57], v[12:13]
	v_lshl_add_u64 v[16:17], v[96:97], 0, s[14:15]
	v_pk_fma_f32 v[22:23], v[62:63], v[18:19], v[8:9] neg_lo:[0,0,1] neg_hi:[0,0,1]
	v_pk_fma_f32 v[8:9], v[60:61], v[20:21], v[10:11] neg_lo:[0,0,1] neg_hi:[0,0,1]
	v_pk_mul_f32 v[10:11], v[58:59], v[18:19]
	v_pk_mul_f32 v[24:25], v[56:57], v[20:21]
	s_mov_b32 s14, 0x50000
	v_pk_fma_f32 v[26:27], v[62:63], v[14:15], v[10:11]
	v_pk_fma_f32 v[10:11], v[60:61], v[12:13], v[24:25]
	v_cvt_pk_bf16_f32 v8, v8, v9
	v_cvt_pk_bf16_f32 v9, v22, v23
	v_add_co_u32_e32 v22, vcc, s14, v96
	v_cvt_pk_bf16_f32 v10, v10, v11
	v_cvt_pk_bf16_f32 v11, v26, v27
	v_addc_co_u32_e32 v23, vcc, 0, v97, vcc
	global_store_dwordx4 v[22:23], v[8:11], off
	s_mov_b64 s[14:15], 0x58000
	v_pk_mul_f32 v[6:7], v[100:101], v[6:7]
	v_pk_mul_f32 v[8:9], v[50:51], v[14:15]
	v_pk_mul_f32 v[10:11], v[48:49], v[12:13]
	v_pk_fma_f32 v[22:23], v[54:55], v[18:19], v[8:9] neg_lo:[0,0,1] neg_hi:[0,0,1]
	v_pk_fma_f32 v[8:9], v[52:53], v[20:21], v[10:11] neg_lo:[0,0,1] neg_hi:[0,0,1]
	v_pk_mul_f32 v[10:11], v[50:51], v[18:19]
	v_pk_mul_f32 v[18:19], v[48:49], v[20:21]
	v_pk_fma_f32 v[14:15], v[54:55], v[14:15], v[10:11]
	v_pk_fma_f32 v[10:11], v[52:53], v[12:13], v[18:19]
	v_cvt_pk_bf16_f32 v8, v8, v9
	v_cvt_pk_bf16_f32 v9, v22, v23
	v_cvt_pk_bf16_f32 v10, v10, v11
	v_cvt_pk_bf16_f32 v11, v14, v15
	global_store_dwordx4 v[16:17], v[8:11], off offset:256
	v_pk_mul_f32 v[12:13], v[188:189], v[0:1]
	v_pk_mul_f32 v[4:5], v[188:189], v[4:5]
	v_pk_mul_f32 v[10:11], v[100:101], v[2:3]
	v_pk_mul_f32 v[2:3], v[40:41], v[12:13]
	v_pk_mul_f32 v[0:1], v[42:43], v[10:11]
	v_lshl_add_u64 v[8:9], v[96:97], 0, s[14:15]
	v_pk_fma_f32 v[14:15], v[46:47], v[6:7], v[0:1] neg_lo:[0,0,1] neg_hi:[0,0,1]
	v_pk_fma_f32 v[0:1], v[44:45], v[4:5], v[2:3] neg_lo:[0,0,1] neg_hi:[0,0,1]
	v_pk_mul_f32 v[2:3], v[42:43], v[6:7]
	v_pk_mul_f32 v[16:17], v[40:41], v[4:5]
	s_mov_b32 s14, 0x58000
	v_pk_fma_f32 v[18:19], v[46:47], v[10:11], v[2:3]
	v_pk_fma_f32 v[2:3], v[44:45], v[12:13], v[16:17]
	v_cvt_pk_bf16_f32 v0, v0, v1
	v_cvt_pk_bf16_f32 v1, v14, v15
	v_add_co_u32_e32 v14, vcc, s14, v96
	v_cvt_pk_bf16_f32 v2, v2, v3
	v_cvt_pk_bf16_f32 v3, v18, v19
	v_addc_co_u32_e32 v15, vcc, 0, v97, vcc
	global_store_dwordx4 v[14:15], v[0:3], off
	s_andn2_b64 vcc, exec, s[6:7]
	s_mov_b64 s[6:7], -1
	v_pk_mul_f32 v[0:1], v[34:35], v[10:11]
	v_pk_mul_f32 v[2:3], v[32:33], v[12:13]
	v_pk_fma_f32 v[14:15], v[38:39], v[6:7], v[0:1] neg_lo:[0,0,1] neg_hi:[0,0,1]
	v_pk_fma_f32 v[0:1], v[36:37], v[4:5], v[2:3] neg_lo:[0,0,1] neg_hi:[0,0,1]
	v_pk_mul_f32 v[2:3], v[34:35], v[6:7]
	v_pk_mul_f32 v[4:5], v[32:33], v[4:5]
	v_pk_fma_f32 v[6:7], v[38:39], v[10:11], v[2:3]
	v_pk_fma_f32 v[2:3], v[36:37], v[12:13], v[4:5]
	v_cvt_pk_bf16_f32 v0, v0, v1
	v_cvt_pk_bf16_f32 v1, v14, v15
	v_cvt_pk_bf16_f32 v2, v2, v3
	v_cvt_pk_bf16_f32 v3, v6, v7
	global_store_dwordx4 v[8:9], v[0:3], off offset:256
	s_cbranch_vccnz .LBB0_192
	s_andn2_b64 vcc, exec, s[12:13]
	s_cbranch_vccnz .LBB0_191
	s_barrier
	s_branch .LBB0_191

.LBB0_247:
	s_cmp_gt_i32 s52, 3
	s_cselect_b64 vcc, -1, 0
	v_mov_b32_e32 v128, 0x3db504f3
	v_cndmask_b32_e32 v164, 1.0, v128, vcc
	v_lshlrev_b32_e32 v128, 8, v157
	v_and_b32_e32 v128, 0x1fff00, v128
	v_mov_b32_e32 v129, v213
	v_lshl_add_u64 v[130:131], v[158:159], 0, v[128:129]
	v_lshl_add_u64 v[128:129], v[160:161], 0, v[128:129]
	global_load_dwordx4 v[176:179], v[130:131], off
	global_load_dwordx4 v[180:183], v[128:129], off
	v_lshlrev_b32_e32 v175, 6, v157
	v_add_u32_e32 v128, 0x400, v175
	v_and_b32_e32 v128, 0x7ffc0, v128
	v_lshlrev_b32_e32 v128, 2, v128
	v_mov_b32_e32 v129, v213
	v_lshl_add_u64 v[130:131], v[158:159], 0, v[128:129]
	v_lshl_add_u64 v[128:129], v[160:161], 0, v[128:129]
	global_load_dwordx4 v[148:151], v[130:131], off
	global_load_dwordx4 v[144:147], v[128:129], off
	v_add_u32_e32 v128, 0x800, v175
	v_and_b32_e32 v128, 0x7ffc0, v128
	v_lshlrev_b32_e32 v128, 2, v128
	v_mov_b32_e32 v129, v213
	v_lshl_add_u64 v[130:131], v[158:159], 0, v[128:129]
	v_lshl_add_u64 v[128:129], v[160:161], 0, v[128:129]
	global_load_dwordx4 v[140:143], v[130:131], off
	global_load_dwordx4 v[136:139], v[128:129], off
	v_add_u32_e32 v128, 0xc00, v175
	v_and_b32_e32 v128, 0x7ffc0, v128
	v_lshlrev_b32_e32 v128, 2, v128
	v_mov_b32_e32 v129, v213
	v_lshl_add_u64 v[130:131], v[158:159], 0, v[128:129]
	v_lshl_add_u64 v[128:129], v[160:161], 0, v[128:129]
	global_load_dwordx4 v[132:135], v[130:131], off
	v_ashrrev_i32_e32 v163, 31, v162
	global_load_dwordx4 v[128:131], v[128:129], off
	v_mov_b32_e32 v235, v213
	v_add_u32_e32 v234, 0x2000, v175
	v_and_b32_e32 v234, 0x7ffc0, v234
	v_lshlrev_b32_e32 v234, 2, v234
	v_lshl_add_u64 v[238:239], v[158:159], 0, v[234:235]
	global_load_dwordx4 v[200:203], v[238:239], off
	v_lshl_add_u64 v[238:239], v[160:161], 0, v[234:235]
	global_load_dwordx4 v[204:207], v[238:239], off
	v_add_u32_e32 v234, 0x2400, v175
	v_and_b32_e32 v234, 0x7ffc0, v234
	v_lshlrev_b32_e32 v234, 2, v234
	v_lshl_add_u64 v[238:239], v[158:159], 0, v[234:235]
	global_load_dwordx4 v[208:211], v[238:239], off
	v_lshl_add_u64 v[238:239], v[160:161], 0, v[234:235]
	global_load_dwordx4 v[216:219], v[238:239], off
	v_add_u32_e32 v234, 0x2800, v175
	v_and_b32_e32 v234, 0x7ffc0, v234
	v_lshlrev_b32_e32 v234, 2, v234
	v_lshl_add_u64 v[238:239], v[158:159], 0, v[234:235]
	global_load_dwordx4 v[220:223], v[238:239], off
	v_lshl_add_u64 v[238:239], v[160:161], 0, v[234:235]
	global_load_dwordx4 v[224:227], v[238:239], off
	v_add_u32_e32 v234, 0x2c00, v175
	v_and_b32_e32 v234, 0x7ffc0, v234
	v_lshlrev_b32_e32 v234, 2, v234
	v_lshl_add_u64 v[238:239], v[158:159], 0, v[234:235]
	global_load_dwordx4 v[228:231], v[238:239], off
	v_lshl_add_u64 v[238:239], v[160:161], 0, v[234:235]
	global_load_dwordx2 v[248:249], v[238:239], off
	global_load_dwordx2 v[196:197], v[238:239], off offset:8
	v_mov_b64_e32 v[166:167], s[12:13]
	s_movk_i32 s22, 0x3000
	v_mad_i64_i32 v[184:185], s[14:15], v157, s22, v[166:167]
	v_lshlrev_b64 v[162:163], 1, v[162:163]
	v_lshl_add_u64 v[184:185], v[184:185], 0, v[162:163]
	s_waitcnt vmcnt(0)
	v_pk_mul_f32 v[176:177], v[164:165], v[176:177] op_sel_hi:[0,1]
	v_pk_mul_f32 v[182:183], v[164:165], v[182:183] op_sel_hi:[0,1]
	v_pk_mul_f32 v[180:181], v[164:165], v[180:181] op_sel_hi:[0,1]
	v_pk_mul_f32 v[178:179], v[164:165], v[178:179] op_sel_hi:[0,1]
	v_pk_mul_f32 v[186:187], v[120:121], v[180:181]
	v_pk_mul_f32 v[188:189], v[122:123], v[182:183]
	v_pk_fma_f32 v[186:187], v[124:125], v[176:177], v[186:187] neg_lo:[0,0,1] neg_hi:[0,0,1]
	v_pk_fma_f32 v[188:189], v[126:127], v[178:179], v[188:189] neg_lo:[0,0,1] neg_hi:[0,0,1]
	v_pk_mul_f32 v[124:125], v[124:125], v[180:181]
	v_pk_mul_f32 v[126:127], v[126:127], v[182:183]
	s_nop 0
	v_pk_fma_f32 v[126:127], v[122:123], v[178:179], v[126:127]
	v_pk_fma_f32 v[122:123], v[120:121], v[176:177], v[124:125]
	v_cvt_pk_bf16_f32 v120, v186, v187
	v_cvt_pk_bf16_f32 v121, v188, v189
	v_cvt_pk_bf16_f32 v122, v122, v123
	v_cvt_pk_bf16_f32 v123, v126, v127
	global_store_dwordx4 v[184:185], v[120:123], off
	s_nop 1
	v_pk_mul_f32 v[120:121], v[112:113], v[180:181]
	v_pk_mul_f32 v[122:123], v[114:115], v[182:183]
	v_pk_fma_f32 v[120:121], v[116:117], v[176:177], v[120:121] neg_lo:[0,0,1] neg_hi:[0,0,1]
	v_pk_fma_f32 v[122:123], v[118:119], v[178:179], v[122:123] neg_lo:[0,0,1] neg_hi:[0,0,1]
	v_pk_mul_f32 v[116:117], v[116:117], v[180:181]
	v_pk_mul_f32 v[118:119], v[118:119], v[182:183]
	s_nop 0
	v_pk_fma_f32 v[118:119], v[114:115], v[178:179], v[118:119]
	v_pk_fma_f32 v[114:115], v[112:113], v[176:177], v[116:117]
	v_cvt_pk_bf16_f32 v112, v120, v121
	v_cvt_pk_bf16_f32 v113, v122, v123
	v_cvt_pk_bf16_f32 v114, v114, v115
	v_cvt_pk_bf16_f32 v115, v118, v119
	v_pk_mul_f32 v[118:119], v[164:165], v[146:147] op_sel_hi:[0,1]
	v_pk_mul_f32 v[120:121], v[164:165], v[144:145] op_sel_hi:[0,1]
	global_store_dwordx4 v[184:185], v[112:115], off offset:256
	v_pk_mul_f32 v[116:117], v[164:165], v[150:151] op_sel_hi:[0,1]
	v_pk_mul_f32 v[122:123], v[104:105], v[120:121]
	v_pk_mul_f32 v[114:115], v[164:165], v[148:149] op_sel_hi:[0,1]
	v_pk_mul_f32 v[124:125], v[106:107], v[118:119]
	v_add_u32_e32 v112, 16, v157
	v_pk_fma_f32 v[124:125], v[110:111], v[116:117], v[124:125] neg_lo:[0,0,1] neg_hi:[0,0,1]
	v_pk_fma_f32 v[122:123], v[108:109], v[114:115], v[122:123] neg_lo:[0,0,1] neg_hi:[0,0,1]
	v_pk_mul_f32 v[108:109], v[108:109], v[120:121]
	v_pk_mul_f32 v[110:111], v[110:111], v[118:119]
	v_mad_i64_i32 v[112:113], s[14:15], v112, s22, v[166:167]
	v_pk_fma_f32 v[110:111], v[106:107], v[116:117], v[110:111]
	v_pk_fma_f32 v[106:107], v[104:105], v[114:115], v[108:109]
	v_lshl_add_u64 v[112:113], v[112:113], 0, v[162:163]
	v_cvt_pk_bf16_f32 v104, v122, v123
	v_cvt_pk_bf16_f32 v105, v124, v125
	v_cvt_pk_bf16_f32 v106, v106, v107
	v_cvt_pk_bf16_f32 v107, v110, v111
	global_store_dwordx4 v[112:113], v[104:107], off
	s_nop 1
	v_pk_mul_f32 v[104:105], v[96:97], v[120:121]
	v_pk_mul_f32 v[106:107], v[98:99], v[118:119]
	v_pk_fma_f32 v[104:105], v[100:101], v[114:115], v[104:105] neg_lo:[0,0,1] neg_hi:[0,0,1]
	v_pk_fma_f32 v[106:107], v[102:103], v[116:117], v[106:107] neg_lo:[0,0,1] neg_hi:[0,0,1]
	v_pk_mul_f32 v[100:101], v[100:101], v[120:121]
	v_pk_mul_f32 v[102:103], v[102:103], v[118:119]
	s_nop 0
	v_pk_fma_f32 v[102:103], v[98:99], v[116:117], v[102:103]
	v_pk_fma_f32 v[98:99], v[96:97], v[114:115], v[100:101]
	v_cvt_pk_bf16_f32 v96, v104, v105
	v_cvt_pk_bf16_f32 v97, v106, v107
	v_cvt_pk_bf16_f32 v98, v98, v99
	v_cvt_pk_bf16_f32 v99, v102, v103
	v_pk_mul_f32 v[102:103], v[164:165], v[138:139] op_sel_hi:[0,1]
	v_pk_mul_f32 v[104:105], v[164:165], v[136:137] op_sel_hi:[0,1]
	global_store_dwordx4 v[112:113], v[96:99], off offset:256
	v_pk_mul_f32 v[100:101], v[164:165], v[142:143] op_sel_hi:[0,1]
	v_pk_mul_f32 v[106:107], v[88:89], v[104:105]
	v_pk_mul_f32 v[98:99], v[164:165], v[140:141] op_sel_hi:[0,1]
	v_pk_mul_f32 v[108:109], v[90:91], v[102:103]
	v_add_u32_e32 v96, 32, v157
	v_pk_fma_f32 v[108:109], v[94:95], v[100:101], v[108:109] neg_lo:[0,0,1] neg_hi:[0,0,1]
	v_pk_fma_f32 v[106:107], v[92:93], v[98:99], v[106:107] neg_lo:[0,0,1] neg_hi:[0,0,1]
	v_pk_mul_f32 v[92:93], v[92:93], v[104:105]
	v_pk_mul_f32 v[94:95], v[94:95], v[102:103]
	v_mad_i64_i32 v[96:97], s[14:15], v96, s22, v[166:167]
	v_pk_fma_f32 v[94:95], v[90:91], v[100:101], v[94:95]
	v_pk_fma_f32 v[90:91], v[88:89], v[98:99], v[92:93]
	v_lshl_add_u64 v[96:97], v[96:97], 0, v[162:163]
	v_cvt_pk_bf16_f32 v88, v106, v107
	v_cvt_pk_bf16_f32 v89, v108, v109
	v_cvt_pk_bf16_f32 v90, v90, v91
	v_cvt_pk_bf16_f32 v91, v94, v95
	global_store_dwordx4 v[96:97], v[88:91], off
	s_nop 1
	v_pk_mul_f32 v[88:89], v[80:81], v[104:105]
	v_pk_mul_f32 v[90:91], v[82:83], v[102:103]
	v_pk_fma_f32 v[88:89], v[84:85], v[98:99], v[88:89] neg_lo:[0,0,1] neg_hi:[0,0,1]
	v_pk_fma_f32 v[90:91], v[86:87], v[100:101], v[90:91] neg_lo:[0,0,1] neg_hi:[0,0,1]
	v_pk_mul_f32 v[84:85], v[84:85], v[104:105]
	v_pk_mul_f32 v[86:87], v[86:87], v[102:103]
	s_nop 0
	v_pk_fma_f32 v[86:87], v[82:83], v[100:101], v[86:87]
	v_pk_fma_f32 v[82:83], v[80:81], v[98:99], v[84:85]
	v_cvt_pk_bf16_f32 v80, v88, v89
	v_cvt_pk_bf16_f32 v81, v90, v91
	v_cvt_pk_bf16_f32 v82, v82, v83
	v_cvt_pk_bf16_f32 v83, v86, v87
	v_pk_mul_f32 v[86:87], v[164:165], v[130:131] op_sel_hi:[0,1]
	v_pk_mul_f32 v[88:89], v[164:165], v[128:129] op_sel_hi:[0,1]
	global_store_dwordx4 v[96:97], v[80:83], off offset:256
	v_pk_mul_f32 v[84:85], v[164:165], v[134:135] op_sel_hi:[0,1]
	v_pk_mul_f32 v[90:91], v[72:73], v[88:89]
	v_pk_mul_f32 v[82:83], v[164:165], v[132:133] op_sel_hi:[0,1]
	v_pk_mul_f32 v[92:93], v[74:75], v[86:87]
	v_add_u32_e32 v80, 48, v157
	v_pk_fma_f32 v[92:93], v[78:79], v[84:85], v[92:93] neg_lo:[0,0,1] neg_hi:[0,0,1]
	v_pk_fma_f32 v[90:91], v[76:77], v[82:83], v[90:91] neg_lo:[0,0,1] neg_hi:[0,0,1]
	v_pk_mul_f32 v[76:77], v[76:77], v[88:89]
	v_pk_mul_f32 v[78:79], v[78:79], v[86:87]
	v_mad_i64_i32 v[80:81], s[14:15], v80, s22, v[166:167]
	v_pk_fma_f32 v[78:79], v[74:75], v[84:85], v[78:79]
	v_pk_fma_f32 v[74:75], v[72:73], v[82:83], v[76:77]
	v_lshl_add_u64 v[80:81], v[80:81], 0, v[162:163]
	v_cvt_pk_bf16_f32 v72, v90, v91
	v_cvt_pk_bf16_f32 v73, v92, v93
	v_cvt_pk_bf16_f32 v74, v74, v75
	v_cvt_pk_bf16_f32 v75, v78, v79
	global_store_dwordx4 v[80:81], v[72:75], off
	v_mov_b32_e32 v77, v213
	v_mov_b32_e32 v93, v213
	v_pk_mul_f32 v[72:73], v[64:65], v[88:89]
	v_pk_mul_f32 v[74:75], v[66:67], v[86:87]
	v_pk_fma_f32 v[72:73], v[68:69], v[82:83], v[72:73] neg_lo:[0,0,1] neg_hi:[0,0,1]
	v_pk_fma_f32 v[74:75], v[70:71], v[84:85], v[74:75] neg_lo:[0,0,1] neg_hi:[0,0,1]
	v_pk_mul_f32 v[68:69], v[68:69], v[88:89]
	v_pk_mul_f32 v[70:71], v[70:71], v[86:87]
	v_add_u32_e32 v88, 0x2c00, v175
	v_pk_fma_f32 v[70:71], v[66:67], v[84:85], v[70:71]
	v_pk_fma_f32 v[66:67], v[64:65], v[82:83], v[68:69]
	v_cvt_pk_bf16_f32 v64, v72, v73
	v_cvt_pk_bf16_f32 v65, v74, v75
	v_cvt_pk_bf16_f32 v66, v66, v67
	v_cvt_pk_bf16_f32 v67, v70, v71
	global_store_dwordx4 v[80:81], v[64:67], off offset:256
	v_add_u32_e32 v96, 0x80, v157
	v_mov_b64_e32 v[68:69], v[204:205]
	v_mov_b64_e32 v[70:71], v[206:207]
	v_mov_b64_e32 v[72:73], v[208:209]
	v_mov_b64_e32 v[74:75], v[210:211]
	v_mov_b64_e32 v[76:77], v[216:217]
	v_mov_b64_e32 v[78:79], v[218:219]
	v_mov_b64_e32 v[80:81], v[220:221]
	v_mov_b64_e32 v[82:83], v[222:223]
	v_mov_b64_e32 v[84:85], v[224:225]
	v_mov_b64_e32 v[86:87], v[226:227]
	v_mov_b64_e32 v[88:89], v[228:229]
	v_mov_b64_e32 v[90:91], v[230:231]
	v_mov_b64_e32 v[92:93], v[248:249]
	v_mov_b64_e32 v[94:95], v[196:197]
	v_mov_b64_e32 v[64:65], v[200:201]
	v_mov_b64_e32 v[66:67], v[202:203]
	v_mad_i64_i32 v[96:97], s[14:15], v96, s22, v[166:167]
	v_lshl_add_u64 v[96:97], v[96:97], 0, v[162:163]
	v_pk_mul_f32 v[64:65], v[164:165], v[64:65] op_sel_hi:[0,1]
	v_pk_mul_f32 v[66:67], v[164:165], v[66:67] op_sel_hi:[0,1]
	v_pk_mul_f32 v[70:71], v[164:165], v[70:71] op_sel_hi:[0,1]
	v_pk_mul_f32 v[68:69], v[164:165], v[68:69] op_sel_hi:[0,1]
	v_pk_mul_f32 v[98:99], v[56:57], v[68:69]
	v_pk_mul_f32 v[100:101], v[58:59], v[70:71]
	v_pk_fma_f32 v[98:99], v[60:61], v[64:65], v[98:99] neg_lo:[0,0,1] neg_hi:[0,0,1]
	v_pk_fma_f32 v[100:101], v[62:63], v[66:67], v[100:101] neg_lo:[0,0,1] neg_hi:[0,0,1]
	v_pk_mul_f32 v[60:61], v[60:61], v[68:69]
	v_pk_mul_f32 v[62:63], v[62:63], v[70:71]
	s_nop 0
	v_pk_fma_f32 v[62:63], v[58:59], v[66:67], v[62:63]
	v_pk_fma_f32 v[58:59], v[56:57], v[64:65], v[60:61]
	v_cvt_pk_bf16_f32 v56, v98, v99
	v_cvt_pk_bf16_f32 v57, v100, v101
	v_cvt_pk_bf16_f32 v58, v58, v59
	v_cvt_pk_bf16_f32 v59, v62, v63
	global_store_dwordx4 v[96:97], v[56:59], off
	s_nop 1
	v_pk_mul_f32 v[56:57], v[48:49], v[68:69]
	v_pk_mul_f32 v[58:59], v[50:51], v[70:71]
	v_pk_fma_f32 v[56:57], v[52:53], v[64:65], v[56:57] neg_lo:[0,0,1] neg_hi:[0,0,1]
	v_pk_fma_f32 v[58:59], v[54:55], v[66:67], v[58:59] neg_lo:[0,0,1] neg_hi:[0,0,1]
	v_pk_mul_f32 v[52:53], v[52:53], v[68:69]
	v_pk_mul_f32 v[54:55], v[54:55], v[70:71]
	s_nop 0
	v_pk_fma_f32 v[54:55], v[50:51], v[66:67], v[54:55]
	v_pk_fma_f32 v[50:51], v[48:49], v[64:65], v[52:53]
	v_cvt_pk_bf16_f32 v48, v56, v57
	v_cvt_pk_bf16_f32 v49, v58, v59
	v_cvt_pk_bf16_f32 v50, v50, v51
	v_cvt_pk_bf16_f32 v51, v54, v55
	v_pk_mul_f32 v[54:55], v[164:165], v[78:79] op_sel_hi:[0,1]
	v_pk_mul_f32 v[56:57], v[164:165], v[76:77] op_sel_hi:[0,1]
	global_store_dwordx4 v[96:97], v[48:51], off offset:256
	v_pk_mul_f32 v[52:53], v[164:165], v[74:75] op_sel_hi:[0,1]
	v_pk_mul_f32 v[58:59], v[40:41], v[56:57]
	v_pk_mul_f32 v[50:51], v[164:165], v[72:73] op_sel_hi:[0,1]
	v_pk_mul_f32 v[60:61], v[42:43], v[54:55]
	v_add_u32_e32 v48, 0x90, v157
	v_pk_fma_f32 v[60:61], v[46:47], v[52:53], v[60:61] neg_lo:[0,0,1] neg_hi:[0,0,1]
	v_pk_fma_f32 v[58:59], v[44:45], v[50:51], v[58:59] neg_lo:[0,0,1] neg_hi:[0,0,1]
	v_pk_mul_f32 v[44:45], v[44:45], v[56:57]
	v_pk_mul_f32 v[46:47], v[46:47], v[54:55]
	v_mad_i64_i32 v[48:49], s[14:15], v48, s22, v[166:167]
	v_pk_fma_f32 v[46:47], v[42:43], v[52:53], v[46:47]
	v_pk_fma_f32 v[42:43], v[40:41], v[50:51], v[44:45]
	v_lshl_add_u64 v[48:49], v[48:49], 0, v[162:163]
	v_cvt_pk_bf16_f32 v40, v58, v59
	v_cvt_pk_bf16_f32 v41, v60, v61
	v_cvt_pk_bf16_f32 v42, v42, v43
	v_cvt_pk_bf16_f32 v43, v46, v47
	global_store_dwordx4 v[48:49], v[40:43], off
	s_nop 1
	v_pk_mul_f32 v[40:41], v[32:33], v[56:57]
	v_pk_mul_f32 v[42:43], v[34:35], v[54:55]
	v_pk_fma_f32 v[40:41], v[36:37], v[50:51], v[40:41] neg_lo:[0,0,1] neg_hi:[0,0,1]
	v_pk_fma_f32 v[42:43], v[38:39], v[52:53], v[42:43] neg_lo:[0,0,1] neg_hi:[0,0,1]
	v_pk_mul_f32 v[36:37], v[36:37], v[56:57]
	v_pk_mul_f32 v[38:39], v[38:39], v[54:55]
	s_nop 0
	v_pk_fma_f32 v[38:39], v[34:35], v[52:53], v[38:39]
	v_pk_fma_f32 v[34:35], v[32:33], v[50:51], v[36:37]
	v_cvt_pk_bf16_f32 v32, v40, v41
	v_cvt_pk_bf16_f32 v33, v42, v43
	v_cvt_pk_bf16_f32 v34, v34, v35
	v_cvt_pk_bf16_f32 v35, v38, v39
	v_pk_mul_f32 v[38:39], v[164:165], v[86:87] op_sel_hi:[0,1]
	v_pk_mul_f32 v[40:41], v[164:165], v[84:85] op_sel_hi:[0,1]
	global_store_dwordx4 v[48:49], v[32:35], off offset:256
	v_pk_mul_f32 v[36:37], v[164:165], v[82:83] op_sel_hi:[0,1]
	v_pk_mul_f32 v[42:43], v[24:25], v[40:41]
	v_pk_mul_f32 v[34:35], v[164:165], v[80:81] op_sel_hi:[0,1]
	v_pk_mul_f32 v[44:45], v[26:27], v[38:39]
	v_add_u32_e32 v32, 0xa0, v157
	v_pk_fma_f32 v[44:45], v[30:31], v[36:37], v[44:45] neg_lo:[0,0,1] neg_hi:[0,0,1]
	v_pk_fma_f32 v[42:43], v[28:29], v[34:35], v[42:43] neg_lo:[0,0,1] neg_hi:[0,0,1]
	v_pk_mul_f32 v[28:29], v[28:29], v[40:41]
	v_pk_mul_f32 v[30:31], v[30:31], v[38:39]
	v_mad_i64_i32 v[32:33], s[14:15], v32, s22, v[166:167]
	v_pk_fma_f32 v[30:31], v[26:27], v[36:37], v[30:31]
	v_pk_fma_f32 v[26:27], v[24:25], v[34:35], v[28:29]
	v_lshl_add_u64 v[32:33], v[32:33], 0, v[162:163]
	v_cvt_pk_bf16_f32 v24, v42, v43
	v_cvt_pk_bf16_f32 v25, v44, v45
	v_cvt_pk_bf16_f32 v26, v26, v27
	v_cvt_pk_bf16_f32 v27, v30, v31
	global_store_dwordx4 v[32:33], v[24:27], off
	s_nop 1
	v_pk_mul_f32 v[24:25], v[16:17], v[40:41]
	v_pk_mul_f32 v[26:27], v[18:19], v[38:39]
	v_pk_fma_f32 v[24:25], v[20:21], v[34:35], v[24:25] neg_lo:[0,0,1] neg_hi:[0,0,1]
	v_pk_fma_f32 v[26:27], v[22:23], v[36:37], v[26:27] neg_lo:[0,0,1] neg_hi:[0,0,1]
	v_pk_mul_f32 v[20:21], v[20:21], v[40:41]
	v_pk_mul_f32 v[22:23], v[22:23], v[38:39]
	s_nop 0
	v_pk_fma_f32 v[22:23], v[18:19], v[36:37], v[22:23]
	v_pk_fma_f32 v[18:19], v[16:17], v[34:35], v[20:21]
	v_cvt_pk_bf16_f32 v16, v24, v25
	v_cvt_pk_bf16_f32 v17, v26, v27
	v_cvt_pk_bf16_f32 v18, v18, v19
	v_cvt_pk_bf16_f32 v19, v22, v23
	v_pk_mul_f32 v[22:23], v[164:165], v[94:95] op_sel_hi:[0,1]
	v_pk_mul_f32 v[24:25], v[164:165], v[92:93] op_sel_hi:[0,1]
	global_store_dwordx4 v[32:33], v[16:19], off offset:256
	v_pk_mul_f32 v[20:21], v[164:165], v[90:91] op_sel_hi:[0,1]
	v_pk_mul_f32 v[26:27], v[8:9], v[24:25]
	v_pk_mul_f32 v[18:19], v[164:165], v[88:89] op_sel_hi:[0,1]
	v_pk_mul_f32 v[28:29], v[10:11], v[22:23]
	v_add_u32_e32 v16, 0xb0, v157
	v_pk_fma_f32 v[28:29], v[14:15], v[20:21], v[28:29] neg_lo:[0,0,1] neg_hi:[0,0,1]
	v_pk_fma_f32 v[26:27], v[12:13], v[18:19], v[26:27] neg_lo:[0,0,1] neg_hi:[0,0,1]
	v_pk_mul_f32 v[12:13], v[12:13], v[24:25]
	v_pk_mul_f32 v[14:15], v[14:15], v[22:23]
	v_mad_i64_i32 v[16:17], s[14:15], v16, s22, v[166:167]
	v_pk_fma_f32 v[14:15], v[10:11], v[20:21], v[14:15]
	v_pk_fma_f32 v[10:11], v[8:9], v[18:19], v[12:13]
	v_lshl_add_u64 v[16:17], v[16:17], 0, v[162:163]
	v_cvt_pk_bf16_f32 v8, v26, v27
	v_cvt_pk_bf16_f32 v9, v28, v29
	v_cvt_pk_bf16_f32 v10, v10, v11
	v_cvt_pk_bf16_f32 v11, v14, v15
	global_store_dwordx4 v[16:17], v[8:11], off
	s_nop 1
	v_pk_mul_f32 v[8:9], v[0:1], v[24:25]
	v_pk_mul_f32 v[10:11], v[2:3], v[22:23]
	v_pk_fma_f32 v[8:9], v[4:5], v[18:19], v[8:9] neg_lo:[0,0,1] neg_hi:[0,0,1]
	v_pk_fma_f32 v[10:11], v[6:7], v[20:21], v[10:11] neg_lo:[0,0,1] neg_hi:[0,0,1]
	v_pk_mul_f32 v[4:5], v[4:5], v[24:25]
	v_pk_mul_f32 v[6:7], v[6:7], v[22:23]
	s_nop 0
	v_pk_fma_f32 v[6:7], v[2:3], v[20:21], v[6:7]
	v_pk_fma_f32 v[2:3], v[0:1], v[18:19], v[4:5]
	v_cvt_pk_bf16_f32 v0, v8, v9
	v_cvt_pk_bf16_f32 v1, v10, v11
	v_cvt_pk_bf16_f32 v2, v2, v3
	v_cvt_pk_bf16_f32 v3, v6, v7
	global_store_dwordx4 v[16:17], v[0:3], off offset:256
	s_andn2_b64 vcc, exec, s[4:5]
	s_mov_b64 s[4:5], -1
	s_cbranch_vccnz .LBB0_229

.LBB0_383:
	v_add_f32_e32 v97, v80, v81
	v_add_f32_e32 v97, v82, v97
	v_add_f32_e32 v97, v83, v97
	v_add_f32_e32 v97, v84, v97
	v_add_f32_e32 v97, v85, v97
	v_add_f32_e32 v97, v86, v97
	v_add_f32_e32 v97, v87, v97
	v_add_f32_e32 v97, v88, v97
	v_add_f32_e32 v97, v89, v97
	v_add_f32_e32 v97, v90, v97
	v_add_f32_e32 v97, v91, v97
	v_add_f32_e32 v97, v92, v97
	v_add_f32_e32 v97, v93, v97
	v_add_f32_e32 v97, v94, v97
	v_add_f32_e32 v97, v95, v97
	v_add_f32_e32 v97, v97, v64
	v_add_f32_e32 v97, v65, v97
	v_add_f32_e32 v97, v66, v97
	v_add_f32_e32 v97, v67, v97
	v_add_f32_e32 v97, v68, v97
	v_add_f32_e32 v97, v69, v97
	v_add_f32_e32 v97, v70, v97
	v_add_f32_e32 v97, v71, v97
	v_add_f32_e32 v97, v72, v97
	v_add_f32_e32 v97, v73, v97
	v_add_f32_e32 v97, v74, v97
	v_add_f32_e32 v97, v75, v97
	v_add_f32_e32 v97, v76, v97
	v_add_f32_e32 v97, v77, v97
	v_add_f32_e32 v97, v78, v97
	v_add_f32_e32 v97, v79, v97
	v_add_f32_e32 v97, v112, v97
	v_cvt_pk_bf16_f32 v64, v64, v65
	v_lshl_add_u32 v98, s66, 1, v244
	v_cvt_pk_bf16_f32 v80, v80, v81
	v_cvt_pk_bf16_f32 v81, v82, v83
	v_cvt_pk_bf16_f32 v82, v84, v85
	v_cvt_pk_bf16_f32 v83, v86, v87
	v_cvt_pk_bf16_f32 v84, v88, v89
	v_cvt_pk_bf16_f32 v85, v90, v91
	v_cvt_pk_bf16_f32 v86, v92, v93
	v_cvt_pk_bf16_f32 v87, v94, v95
	v_cvt_pk_bf16_f32 v65, v66, v67
	v_cvt_pk_bf16_f32 v66, v68, v69
	v_cvt_pk_bf16_f32 v67, v70, v71
	v_cvt_pk_bf16_f32 v68, v72, v73
	v_cvt_pk_bf16_f32 v69, v74, v75
	v_cvt_pk_bf16_f32 v70, v76, v77
	v_cvt_pk_bf16_f32 v71, v78, v79
	v_add_u32_e32 v98, 0x6000, v98
	ds_read_b64_tr_b16 v[72:73],v98 offset:0
	ds_read_b64_tr_b16 v[74:75],v98 offset:512
	ds_read_b64_tr_b16 v[76:77],v98 offset:1024
	ds_read_b64_tr_b16 v[78:79],v98 offset:1536
	ds_read_b64_tr_b16 v[88:89],v98 offset:2048
	ds_read_b64_tr_b16 v[90:91],v98 offset:2560
	ds_read_b64_tr_b16 v[92:93],v98 offset:3072
	ds_read_b64_tr_b16 v[94:95],v98 offset:3584
	s_waitcnt lgkmcnt(0)
	s_nop 0
	v_mfma_f32_32x32x16_bf16 v[32:47], v[80:83], v[72:75], v[32:47]
	ds_read_b64_tr_b16 v[72:73],v98 offset:4096
	ds_read_b64_tr_b16 v[74:75],v98 offset:4608
	v_mfma_f32_32x32x16_bf16 v[32:47], v[84:87], v[76:79], v[32:47]
	ds_read_b64_tr_b16 v[76:77],v98 offset:5120
	ds_read_b64_tr_b16 v[78:79],v98 offset:5632
	v_mfma_f32_32x32x16_bf16 v[32:47], v[64:67], v[88:91], v[32:47]
	ds_read_b64_tr_b16 v[88:89],v98 offset:6144
	ds_read_b64_tr_b16 v[90:91],v98 offset:6656
	v_mfma_f32_32x32x16_bf16 v[32:47], v[68:71], v[92:95], v[32:47]
	ds_read_b64_tr_b16 v[92:93],v98 offset:7168
	ds_read_b64_tr_b16 v[94:95],v98 offset:7680
	s_waitcnt lgkmcnt(0)
	v_mfma_f32_32x32x16_bf16 v[48:63], v[80:83], v[72:75], v[48:63]
	ds_read_b64_tr_b16 v[72:73],v98 offset:8192
	ds_read_b64_tr_b16 v[74:75],v98 offset:8704
	v_mfma_f32_32x32x16_bf16 v[48:63], v[84:87], v[76:79], v[48:63]
	ds_read_b64_tr_b16 v[76:77],v98 offset:9216
	ds_read_b64_tr_b16 v[78:79],v98 offset:9728
	v_mfma_f32_32x32x16_bf16 v[48:63], v[64:67], v[88:91], v[48:63]
	ds_read_b64_tr_b16 v[88:89],v98 offset:10240
	ds_read_b64_tr_b16 v[90:91],v98 offset:10752
	v_mfma_f32_32x32x16_bf16 v[48:63], v[68:71], v[92:95], v[48:63]
	ds_read_b64_tr_b16 v[92:93],v98 offset:11264
	ds_read_b64_tr_b16 v[94:95],v98 offset:11776
	s_waitcnt lgkmcnt(0)
	v_mfma_f32_32x32x16_bf16 v[16:31], v[80:83], v[72:75], v[16:31]
	ds_read_b64_tr_b16 v[72:73],v98 offset:12288
	ds_read_b64_tr_b16 v[74:75],v98 offset:12800
	v_mfma_f32_32x32x16_bf16 v[16:31], v[84:87], v[76:79], v[16:31]
	ds_read_b64_tr_b16 v[76:77],v98 offset:13312
	ds_read_b64_tr_b16 v[78:79],v98 offset:13824
	v_mfma_f32_32x32x16_bf16 v[16:31], v[64:67], v[88:91], v[16:31]
	ds_read_b64_tr_b16 v[88:89],v98 offset:14336
	ds_read_b64_tr_b16 v[90:91],v98 offset:14848
	v_mfma_f32_32x32x16_bf16 v[16:31], v[68:71], v[92:95], v[16:31]
	ds_read_b64_tr_b16 v[92:93],v98 offset:15360
	ds_read_b64_tr_b16 v[94:95],v98 offset:15872
	s_waitcnt lgkmcnt(0)
	v_mfma_f32_32x32x16_bf16 v[0:15], v[80:83], v[72:75], v[0:15]
	v_cmp_gt_u32_e32 vcc, 32, v239
	v_mfma_f32_32x32x16_bf16 v[0:15], v[84:87], v[76:79], v[0:15]
	v_mfma_f32_32x32x16_bf16 v[0:15], v[64:67], v[88:91], v[0:15]
	v_mov_b32_e32 v64, v97
	s_nop 1
	v_permlane32_swap_b32_e32 v97, v64
	v_mfma_f32_32x32x16_bf16 v[0:15], v[68:71], v[92:95], v[0:15]
	s_and_saveexec_b64 s[2:3], vcc
	v_add_f32_e32 v64, v97, v64
	ds_write_b32 v243, v64 offset:128
	s_or_b64 exec, exec, s[2:3]
	s_waitcnt lgkmcnt(0)
	ds_read_b128 v[64:67], v96 offset:128
	ds_read_b128 v[68:71], v96 offset:160
	s_lshl_b32 s2, s55, 7
	s_lshl_b64 s[4:5], s[78:79], 12
	s_add_u32 s4, s52, s4
	s_waitcnt lgkmcnt(1)
	v_rcp_f32_e32 v72, v64
	v_rcp_f32_e32 v73, v65
	v_rcp_f32_e32 v74, v66
	v_rcp_f32_e32 v75, v67
	s_waitcnt lgkmcnt(0)
	v_rcp_f32_e32 v76, v68
	ds_read_b128 v[64:67], v96 offset:192
	v_rcp_f32_e32 v77, v69
	v_rcp_f32_e32 v78, v70
	v_rcp_f32_e32 v79, v71
	ds_read_b128 v[68:71], v96 offset:224
	s_addc_u32 s5, s53, s5
	s_ashr_i32 s3, s2, 31
	s_lshl_b64 s[2:3], s[2:3], 1
	s_waitcnt lgkmcnt(1)
	v_rcp_f32_e32 v64, v64
	v_rcp_f32_e32 v65, v65
	v_rcp_f32_e32 v66, v66
	v_rcp_f32_e32 v67, v67
	s_waitcnt lgkmcnt(0)
	v_rcp_f32_e32 v68, v68
	v_rcp_f32_e32 v69, v69
	v_rcp_f32_e32 v70, v70
	v_rcp_f32_e32 v71, v71
	s_add_u32 s2, s4, s2
	s_addc_u32 s3, s5, s3
	s_bitcmp1_b32 s55, 0
	s_cselect_b64 s[14:15], -1, 0
	v_lshlrev_b32_e32 v165, 7, v242
	s_mov_b64 s[4:5], -1
	s_and_b64 vcc, exec, s[14:15]
	v_lshl_add_u32 v122, v241, 1, s88
	v_mul_f32_e32 v167, v32, v72
	v_mul_f32_e32 v166, v48, v72
	v_mul_f32_e32 v164, v33, v73
	v_mul_f32_e32 v163, v49, v73
	v_mul_f32_e32 v162, v34, v74
	v_mul_f32_e32 v161, v50, v74
	v_mul_f32_e32 v160, v35, v75
	v_mul_f32_e32 v159, v51, v75
	v_or_b32_e32 v157, 0x400, v165
	v_mul_f32_e32 v158, v36, v76
	v_mul_f32_e32 v156, v52, v76
	v_or_b32_e32 v154, 0x480, v165
	v_mul_f32_e32 v155, v37, v77
	v_mul_f32_e32 v153, v53, v77
	v_or_b32_e32 v151, 0x500, v165
	v_mul_f32_e32 v152, v38, v78
	v_mul_f32_e32 v150, v54, v78
	v_or_b32_e32 v148, 0x580, v165
	v_mul_f32_e32 v149, v39, v79
	v_mul_f32_e32 v147, v55, v79
	v_or_b32_e32 v145, 0x800, v165
	v_mul_f32_e32 v146, v40, v64
	v_mul_f32_e32 v144, v56, v64
	v_or_b32_e32 v142, 0x880, v165
	v_mul_f32_e32 v143, v41, v65
	v_mul_f32_e32 v141, v57, v65
	v_or_b32_e32 v139, 0x900, v165
	v_mul_f32_e32 v140, v42, v66
	v_mul_f32_e32 v138, v58, v66
	v_or_b32_e32 v136, 0x980, v165
	v_mul_f32_e32 v137, v43, v67
	v_mul_f32_e32 v135, v59, v67
	v_or_b32_e32 v133, 0xc00, v165
	v_mul_f32_e32 v134, v44, v68
	v_mul_f32_e32 v132, v60, v68
	v_or_b32_e32 v130, 0xc80, v165
	v_mul_f32_e32 v131, v45, v69
	v_mul_f32_e32 v129, v61, v69
	v_or_b32_e32 v127, 0xd00, v165
	v_mul_f32_e32 v128, v46, v70
	v_mul_f32_e32 v126, v62, v70
	v_or_b32_e32 v124, 0xd80, v165
	v_mul_f32_e32 v125, v47, v71
	v_mul_f32_e32 v123, v63, v71
	v_mul_f32_e32 v121, v16, v72
	v_mul_f32_e32 v120, v0, v72
	v_mul_f32_e32 v119, v17, v73
	v_mul_f32_e32 v118, v1, v73
	v_mul_f32_e32 v117, v18, v74
	v_mul_f32_e32 v116, v2, v74
	v_mul_f32_e32 v115, v19, v75
	v_mul_f32_e32 v114, v3, v75
	v_mul_f32_e32 v113, v20, v76
	v_mul_f32_e32 v112, v4, v76
	v_mul_f32_e32 v111, v21, v77
	v_mul_f32_e32 v110, v5, v77
	v_mul_f32_e32 v109, v22, v78
	v_mul_f32_e32 v108, v6, v78
	v_mul_f32_e32 v107, v23, v79
	v_mul_f32_e32 v106, v7, v79
	v_mul_f32_e32 v105, v24, v64
	v_mul_f32_e32 v104, v8, v64
	v_mul_f32_e32 v103, v25, v65
	v_mul_f32_e32 v102, v9, v65
	v_mul_f32_e32 v101, v26, v66
	v_mul_f32_e32 v100, v10, v66
	v_mul_f32_e32 v99, v27, v67
	v_mul_f32_e32 v98, v11, v67
	v_mul_f32_e32 v97, v28, v68
	v_mul_f32_e32 v96, v12, v68
	v_mul_f32_e32 v95, v29, v69
	v_mul_f32_e32 v94, v13, v69
	v_mul_f32_e32 v93, v30, v70
	v_mul_f32_e32 v92, v14, v70
	v_mul_f32_e32 v91, v31, v71
	v_mul_f32_e32 v90, v15, v71
	s_cbranch_vccz .LBB0_387
	v_and_b32_e32 v72, 56, v240
	v_lshlrev_b32_e32 v2, 4, v239
	v_lshlrev_b32_e32 v212, 1, v72
	v_and_b32_e32 v2, 0x380, v2
	s_movk_i32 s4, 0xff00
	v_add3_u32 v64, s88, v2, v212
	v_lshlrev_b32_e32 v2, 9, v239
	v_lshl_add_u64 v[24:25], s[2:3], 0, v[212:213]
	s_mov_b32 s5, -1
	v_and_b32_e32 v2, 0x7000, v2
	v_lshl_add_u64 v[0:1], v[24:25], 0, s[4:5]
	v_mov_b32_e32 v3, v213
	v_or_b32_e32 v28, 0x8000, v2
	v_mov_b32_e32 v29, v213
	v_lshl_add_u64 v[26:27], v[0:1], 0, v[2:3]
	v_lshl_add_u64 v[4:5], v[0:1], 0, v[28:29]
	v_or_b32_e32 v30, 0x10000, v2
	v_mov_b32_e32 v31, v213
	v_or_b32_e32 v48, 0x18000, v2
	v_mov_b32_e32 v49, v213
	global_load_dwordx4 v[32:35], v[26:27], off
	global_load_dwordx4 v[16:19], v[4:5], off
	v_lshl_add_u64 v[4:5], v[0:1], 0, v[30:31]
	v_lshl_add_u64 v[0:1], v[0:1], 0, v[48:49]
	global_load_dwordx4 v[8:11], v[4:5], off
	v_add_u32_e32 v50, v122, v165
	global_load_dwordx4 v[0:3], v[0:1], off
	v_cvt_pk_bf16_f32 v4, v167, s0
	ds_write_b16 v50, v4
	v_cvt_pk_bf16_f32 v4, v166, s0
	ds_write_b16 v50, v4 offset:64
	v_cvt_pk_bf16_f32 v4, v164, s0
	ds_write_b16 v50, v4 offset:128
	v_cvt_pk_bf16_f32 v4, v163, s0
	ds_write_b16 v50, v4 offset:192
	v_cvt_pk_bf16_f32 v4, v162, s0
	ds_write_b16 v50, v4 offset:256
	v_cvt_pk_bf16_f32 v4, v161, s0
	ds_write_b16 v50, v4 offset:320
	v_cvt_pk_bf16_f32 v4, v160, s0
	ds_write_b16 v50, v4 offset:384
	v_cvt_pk_bf16_f32 v4, v159, s0
	ds_write_b16 v50, v4 offset:448
	v_add_u32_e32 v51, v122, v157
	v_cvt_pk_bf16_f32 v4, v158, s0
	ds_write_b16 v51, v4
	v_cvt_pk_bf16_f32 v4, v156, s0
	ds_write_b16 v51, v4 offset:64
	v_add_u32_e32 v52, v122, v154
	v_cvt_pk_bf16_f32 v4, v155, s0
	ds_write_b16 v52, v4
	v_cvt_pk_bf16_f32 v4, v153, s0
	ds_write_b16 v52, v4 offset:64
	v_add_u32_e32 v53, v122, v151
	v_cvt_pk_bf16_f32 v4, v152, s0
	ds_write_b16 v53, v4
	v_cvt_pk_bf16_f32 v4, v150, s0
	ds_write_b16 v53, v4 offset:64
	v_add_u32_e32 v54, v122, v148
	v_cvt_pk_bf16_f32 v4, v149, s0
	ds_write_b16 v54, v4
	v_cvt_pk_bf16_f32 v4, v147, s0
	ds_write_b16 v54, v4 offset:64
	v_add_u32_e32 v55, v122, v145
	v_cvt_pk_bf16_f32 v4, v146, s0
	ds_write_b16 v55, v4
	v_cvt_pk_bf16_f32 v4, v144, s0
	ds_write_b16 v55, v4 offset:64
	v_add_u32_e32 v56, v122, v142
	v_cvt_pk_bf16_f32 v4, v143, s0
	ds_write_b16 v56, v4
	v_cvt_pk_bf16_f32 v4, v141, s0
	ds_write_b16 v56, v4 offset:64
	v_add_u32_e32 v57, v122, v139
	v_cvt_pk_bf16_f32 v4, v140, s0
	ds_write_b16 v57, v4
	v_cvt_pk_bf16_f32 v4, v138, s0
	ds_write_b16 v57, v4 offset:64
	v_add_u32_e32 v58, v122, v136
	v_cvt_pk_bf16_f32 v4, v137, s0
	ds_write_b16 v58, v4
	v_cvt_pk_bf16_f32 v4, v135, s0
	ds_write_b16 v58, v4 offset:64
	v_add_u32_e32 v59, v122, v133
	v_cvt_pk_bf16_f32 v4, v134, s0
	ds_write_b16 v59, v4
	v_cvt_pk_bf16_f32 v4, v132, s0
	ds_write_b16 v59, v4 offset:64
	v_add_u32_e32 v60, v122, v130
	v_cvt_pk_bf16_f32 v4, v131, s0
	ds_write_b16 v60, v4
	v_cvt_pk_bf16_f32 v4, v129, s0
	ds_write_b16 v60, v4 offset:64
	v_add_u32_e32 v61, v122, v127
	v_cvt_pk_bf16_f32 v4, v128, s0
	ds_write_b16 v61, v4
	v_cvt_pk_bf16_f32 v4, v126, s0
	ds_write_b16 v61, v4 offset:64
	v_add_u32_e32 v62, v122, v124
	v_cvt_pk_bf16_f32 v4, v125, s0
	ds_write_b16 v62, v4
	v_cvt_pk_bf16_f32 v4, v123, s0
	ds_write_b16 v62, v4 offset:64
	s_waitcnt lgkmcnt(0)
	ds_read_b128 v[36:39], v64
	ds_read_b128 v[20:23], v64 offset:1024
	ds_read_b128 v[12:15], v64 offset:2048
	ds_read_b128 v[4:7], v64 offset:3072
	s_waitcnt lgkmcnt(0)
	global_load_dwordx4 v[44:47], v[26:27], off offset:128
	s_movk_i32 s4, 0xff80
	s_mov_b32 s5, -1
	v_lshl_add_u64 v[24:25], v[24:25], 0, s[4:5]
	v_lshl_add_u64 v[26:27], v[24:25], 0, v[28:29]
	global_load_dwordx4 v[40:43], v[26:27], off
	v_lshl_add_u64 v[26:27], v[24:25], 0, v[30:31]
	global_load_dwordx4 v[28:31], v[26:27], off
	v_lshl_add_u64 v[24:25], v[24:25], 0, v[48:49]
	global_load_dwordx4 v[24:27], v[24:25], off
	v_cvt_pk_bf16_f32 v48, v121, s0
	ds_write_b16 v50, v48
	v_cvt_pk_bf16_f32 v48, v120, s0
	ds_write_b16 v50, v48 offset:64
	v_cvt_pk_bf16_f32 v48, v119, s0
	ds_write_b16 v50, v48 offset:128
	v_cvt_pk_bf16_f32 v48, v118, s0
	ds_write_b16 v50, v48 offset:192
	v_cvt_pk_bf16_f32 v48, v117, s0
	ds_write_b16 v50, v48 offset:256
	v_cvt_pk_bf16_f32 v48, v116, s0
	ds_write_b16 v50, v48 offset:320
	v_cvt_pk_bf16_f32 v48, v115, s0
	ds_write_b16 v50, v48 offset:384
	v_cvt_pk_bf16_f32 v48, v114, s0
	ds_write_b16 v50, v48 offset:448
	v_cvt_pk_bf16_f32 v48, v113, s0
	ds_write_b16 v51, v48
	v_cvt_pk_bf16_f32 v48, v112, s0
	ds_write_b16 v51, v48 offset:64
	v_cvt_pk_bf16_f32 v48, v111, s0
	ds_write_b16 v52, v48
	v_cvt_pk_bf16_f32 v48, v110, s0
	ds_write_b16 v52, v48 offset:64
	v_cvt_pk_bf16_f32 v48, v109, s0
	ds_write_b16 v53, v48
	v_cvt_pk_bf16_f32 v48, v108, s0
	ds_write_b16 v53, v48 offset:64
	v_cvt_pk_bf16_f32 v48, v107, s0
	ds_write_b16 v54, v48
	v_cvt_pk_bf16_f32 v48, v106, s0
	ds_write_b16 v54, v48 offset:64
	v_cvt_pk_bf16_f32 v48, v105, s0
	ds_write_b16 v55, v48
	v_cvt_pk_bf16_f32 v48, v104, s0
	ds_write_b16 v55, v48 offset:64
	v_cvt_pk_bf16_f32 v48, v103, s0
	ds_write_b16 v56, v48
	v_cvt_pk_bf16_f32 v48, v102, s0
	ds_write_b16 v56, v48 offset:64
	v_cvt_pk_bf16_f32 v48, v101, s0
	ds_write_b16 v57, v48
	v_cvt_pk_bf16_f32 v48, v100, s0
	ds_write_b16 v57, v48 offset:64
	v_cvt_pk_bf16_f32 v48, v99, s0
	ds_write_b16 v58, v48
	v_cvt_pk_bf16_f32 v48, v98, s0
	ds_write_b16 v58, v48 offset:64
	v_cvt_pk_bf16_f32 v48, v97, s0
	ds_write_b16 v59, v48
	v_cvt_pk_bf16_f32 v48, v96, s0
	ds_write_b16 v59, v48 offset:64
	v_cvt_pk_bf16_f32 v48, v95, s0
	ds_write_b16 v60, v48
	v_cvt_pk_bf16_f32 v48, v94, s0
	ds_write_b16 v60, v48 offset:64
	v_cvt_pk_bf16_f32 v48, v93, s0
	ds_write_b16 v61, v48
	v_cvt_pk_bf16_f32 v48, v92, s0
	ds_write_b16 v61, v48 offset:64
	v_cvt_pk_bf16_f32 v48, v91, s0
	ds_write_b16 v62, v48
	v_cvt_pk_bf16_f32 v48, v90, s0
	ds_write_b16 v62, v48 offset:64
	s_waitcnt lgkmcnt(0)
	ds_read_b128 v[50:53], v64
	v_lshlrev_b32_e32 v168, 2, v72
	s_waitcnt vmcnt(7)
	v_lshlrev_b32_e32 v172, 16, v35
	v_and_b32_e32 v173, 0xffff0000, v35
	v_lshlrev_b32_e32 v176, 16, v34
	s_waitcnt vmcnt(3)
	v_lshlrev_b32_e32 v49, 16, v45
	v_lshlrev_b32_e32 v48, 16, v44
	v_and_b32_e32 v45, 0xffff0000, v45
	v_and_b32_e32 v44, 0xffff0000, v44
	s_waitcnt lgkmcnt(0)
	v_lshlrev_b32_e32 v55, 16, v51
	v_lshlrev_b32_e32 v54, 16, v50
	v_and_b32_e32 v57, 0xffff0000, v51
	v_and_b32_e32 v56, 0xffff0000, v50
	v_pk_fma_f32 v[50:51], s[10:11], v[54:55], v[48:49] neg_lo:[1,0,0] neg_hi:[1,0,0]
	v_pk_fma_f32 v[48:49], s[10:11], v[56:57], v[44:45] neg_lo:[1,0,0] neg_hi:[1,0,0]
	v_and_b32_e32 v55, 0xffff0000, v47
	v_pk_mul_f32 v[44:45], v[48:49], v[48:49]
	v_and_b32_e32 v54, 0xffff0000, v46
	v_pk_fma_f32 v[86:87], v[50:51], v[50:51], v[44:45]
	v_lshlrev_b32_e32 v45, 16, v47
	v_lshlrev_b32_e32 v44, 16, v46
	v_lshlrev_b32_e32 v47, 16, v53
	v_lshlrev_b32_e32 v46, 16, v52
	v_and_b32_e32 v53, 0xffff0000, v53
	v_and_b32_e32 v52, 0xffff0000, v52
	v_pk_fma_f32 v[46:47], s[10:11], v[46:47], v[44:45] neg_lo:[1,0,0] neg_hi:[1,0,0]
	v_pk_fma_f32 v[44:45], s[10:11], v[52:53], v[54:55] neg_lo:[1,0,0] neg_hi:[1,0,0]
	s_waitcnt vmcnt(2)
	v_lshlrev_b32_e32 v57, 16, v41
	v_pk_mul_f32 v[52:53], v[44:45], v[44:45]
	v_lshlrev_b32_e32 v56, 16, v40
	v_pk_fma_f32 v[88:89], v[46:47], v[46:47], v[52:53]
	ds_read_b128 v[52:55], v64 offset:1024
	v_and_b32_e32 v41, 0xffff0000, v41
	v_and_b32_e32 v40, 0xffff0000, v40
	s_waitcnt vmcnt(0)
	v_lshlrev_b32_e32 v65, 16, v25
	v_and_b32_e32 v25, 0xffff0000, v25
	s_waitcnt lgkmcnt(0)
	v_and_b32_e32 v61, 0xffff0000, v53
	v_and_b32_e32 v60, 0xffff0000, v52
	v_lshlrev_b32_e32 v59, 16, v53
	v_lshlrev_b32_e32 v58, 16, v52
	v_pk_fma_f32 v[40:41], s[10:11], v[60:61], v[40:41] neg_lo:[1,0,0] neg_hi:[1,0,0]
	v_pk_fma_f32 v[52:53], s[10:11], v[58:59], v[56:57] neg_lo:[1,0,0] neg_hi:[1,0,0]
	v_pk_mul_f32 v[56:57], v[40:41], v[40:41]
	v_lshlrev_b32_e32 v59, 16, v55
	v_pk_fma_f32 v[82:83], v[52:53], v[52:53], v[56:57]
	v_lshlrev_b32_e32 v57, 16, v43
	v_lshlrev_b32_e32 v56, 16, v42
	v_lshlrev_b32_e32 v58, 16, v54
	v_pk_fma_f32 v[62:63], s[10:11], v[58:59], v[56:57] neg_lo:[1,0,0] neg_hi:[1,0,0]
	ds_read_b128 v[56:59], v64 offset:2048
	v_and_b32_e32 v43, 0xffff0000, v43
	v_and_b32_e32 v42, 0xffff0000, v42
	v_and_b32_e32 v55, 0xffff0000, v55
	v_and_b32_e32 v54, 0xffff0000, v54
	v_pk_fma_f32 v[60:61], s[10:11], v[54:55], v[42:43] neg_lo:[1,0,0] neg_hi:[1,0,0]
	s_waitcnt lgkmcnt(0)
	v_lshlrev_b32_e32 v55, 16, v57
	v_pk_mul_f32 v[42:43], v[60:61], v[60:61]
	v_lshlrev_b32_e32 v54, 16, v56
	v_pk_fma_f32 v[84:85], v[62:63], v[62:63], v[42:43]
	v_lshlrev_b32_e32 v43, 16, v29
	v_lshlrev_b32_e32 v42, 16, v28
	v_and_b32_e32 v29, 0xffff0000, v29
	v_and_b32_e32 v28, 0xffff0000, v28
	v_and_b32_e32 v67, 0xffff0000, v57
	v_and_b32_e32 v66, 0xffff0000, v56
	v_pk_fma_f32 v[56:57], s[10:11], v[54:55], v[42:43] neg_lo:[1,0,0] neg_hi:[1,0,0]
	v_pk_fma_f32 v[54:55], s[10:11], v[66:67], v[28:29] neg_lo:[1,0,0] neg_hi:[1,0,0]
	v_lshlrev_b32_e32 v43, 16, v59
	v_pk_mul_f32 v[28:29], v[54:55], v[54:55]
	v_lshlrev_b32_e32 v42, 16, v58
	v_pk_fma_f32 v[78:79], v[56:57], v[56:57], v[28:29]
	v_lshlrev_b32_e32 v29, 16, v31
	v_lshlrev_b32_e32 v28, 16, v30
	v_and_b32_e32 v31, 0xffff0000, v31
	v_and_b32_e32 v30, 0xffff0000, v30
	v_and_b32_e32 v67, 0xffff0000, v59
	v_and_b32_e32 v66, 0xffff0000, v58
	v_pk_fma_f32 v[58:59], s[10:11], v[42:43], v[28:29] neg_lo:[1,0,0] neg_hi:[1,0,0]
	v_pk_fma_f32 v[42:43], s[10:11], v[66:67], v[30:31] neg_lo:[1,0,0] neg_hi:[1,0,0]
	v_and_b32_e32 v177, 0xffff0000, v34
	v_pk_mul_f32 v[28:29], v[42:43], v[42:43]
	v_lshlrev_b32_e32 v34, 16, v38
	v_pk_fma_f32 v[80:81], v[58:59], v[58:59], v[28:29]
	ds_read_b128 v[28:31], v64 offset:3072
	v_lshlrev_b32_e32 v64, 16, v24
	v_and_b32_e32 v24, 0xffff0000, v24
	s_waitcnt lgkmcnt(0)
	v_and_b32_e32 v35, 0xffff0000, v38
	s_waitcnt lgkmcnt(0)
	v_lshlrev_b32_e32 v67, 16, v29
	v_lshlrev_b32_e32 v66, 16, v28
	v_and_b32_e32 v29, 0xffff0000, v29
	v_and_b32_e32 v28, 0xffff0000, v28
	v_pk_fma_f32 v[66:67], s[10:11], v[66:67], v[64:65] neg_lo:[1,0,0] neg_hi:[1,0,0]
	v_pk_fma_f32 v[64:65], s[10:11], v[28:29], v[24:25] neg_lo:[1,0,0] neg_hi:[1,0,0]
	v_lshlrev_b32_e32 v29, 16, v31
	v_pk_mul_f32 v[24:25], v[64:65], v[64:65]
	v_lshlrev_b32_e32 v28, 16, v30
	v_pk_fma_f32 v[74:75], v[66:67], v[66:67], v[24:25]
	v_lshlrev_b32_e32 v25, 16, v27
	v_lshlrev_b32_e32 v24, 16, v26
	v_and_b32_e32 v27, 0xffff0000, v27
	v_and_b32_e32 v26, 0xffff0000, v26
	v_and_b32_e32 v31, 0xffff0000, v31
	v_and_b32_e32 v30, 0xffff0000, v30
	v_pk_fma_f32 v[68:69], s[10:11], v[30:31], v[26:27] neg_lo:[1,0,0] neg_hi:[1,0,0]
	v_pk_fma_f32 v[70:71], s[10:11], v[28:29], v[24:25] neg_lo:[1,0,0] neg_hi:[1,0,0]
	v_pk_mul_f32 v[24:25], v[68:69], v[68:69]
	v_lshlrev_b32_e32 v174, 16, v39
	v_pk_fma_f32 v[76:77], v[70:71], v[70:71], v[24:25]
	v_lshlrev_b32_e32 v24, 2, v239
	v_xor_b32_e32 v171, 4, v24
	v_xor_b32_e32 v170, 8, v24
	v_xor_b32_e32 v169, 16, v24
	global_load_dwordx4 v[24:27], v168, s[8:9] offset:16
	global_load_dwordx4 v[28:31], v168, s[8:9]
	global_load_dwordx4 v[200:203], v168, s[8:9] offset:272
	global_load_dwordx4 v[204:207], v168, s[8:9] offset:256
	v_and_b32_e32 v175, 0xffff0000, v39
	v_pk_fma_f32 v[34:35], s[10:11], v[34:35], v[176:177] neg_lo:[1,0,0] neg_hi:[1,0,0]
	v_lshlrev_b32_e32 v176, 16, v33
	v_and_b32_e32 v177, 0xffff0000, v33
	v_lshlrev_b32_e32 v178, 16, v37
	v_and_b32_e32 v179, 0xffff0000, v37
	v_lshlrev_b32_e32 v180, 16, v32
	v_and_b32_e32 v181, 0xffff0000, v32
	v_lshlrev_b32_e32 v32, 16, v36
	v_and_b32_e32 v33, 0xffff0000, v36
	v_pk_fma_f32 v[172:173], s[10:11], v[174:175], v[172:173] neg_lo:[1,0,0] neg_hi:[1,0,0]
	v_pk_fma_f32 v[176:177], s[10:11], v[178:179], v[176:177] neg_lo:[1,0,0] neg_hi:[1,0,0]
	v_pk_fma_f32 v[36:37], s[10:11], v[32:33], v[180:181] neg_lo:[1,0,0] neg_hi:[1,0,0]
	v_pk_mul_f32 v[174:175], v[172:173], v[172:173]
	v_pk_mul_f32 v[178:179], v[176:177], v[176:177]
	v_pk_mul_f32 v[32:33], v[36:37], v[36:37]
	v_pk_mul_f32 v[38:39], v[34:35], v[34:35]
	v_add_f32_e32 v174, v174, v175
	v_add_f32_e32 v175, v178, v179
	v_add_f32_e32 v32, v32, v33
	v_add_f32_e32 v32, v32, v175
	v_add_f32_e32 v33, v38, v39
	v_add_f32_e32 v32, v33, v32
	v_add_f32_e32 v32, v174, v32
	v_add_f32_e32 v32, v32, v86
	v_add_f32_e32 v32, v87, v32
	v_add_f32_e32 v32, v88, v32
	v_add_f32_e32 v32, v89, v32
	ds_bpermute_b32 v33, v171, v32
	s_lshl_b64 s[4:5], s[20:21], 1
	v_readlane_b32 s14, v255, 0
	s_add_u32 s4, s14, s4
	v_readlane_b32 s14, v255, 2
	s_waitcnt lgkmcnt(0)
	v_add_f32_e32 v32, v32, v33
	ds_bpermute_b32 v33, v170, v32
	s_addc_u32 s5, s14, s5
	s_add_u32 s4, s4, s96
	s_addc_u32 s5, s5, s97
	v_lshl_add_u64 v[72:73], s[4:5], 0, v[212:213]
	s_waitcnt lgkmcnt(0)
	v_add_f32_e32 v32, v32, v33
	ds_bpermute_b32 v33, v169, v32
	v_lshlrev_b32_e32 v86, 16, v18
	v_and_b32_e32 v87, 0xffff0000, v18
	v_lshlrev_b32_e32 v18, 16, v22
	v_lshlrev_b32_e32 v88, 16, v21
	s_waitcnt lgkmcnt(0)
	v_add_f32_e32 v32, v32, v33
	v_fmamk_f32 v32, v32, 0x3c000000, v251
	v_rsq_f32_e32 v32, v32
	v_and_b32_e32 v89, 0xffff0000, v21
	s_mov_b64 s[4:5], 0
	v_mul_f32_e32 v32, v238, v32
	v_pk_mul_f32 v[36:37], v[36:37], v[32:33] op_sel_hi:[1,0]
	v_pk_mul_f32 v[38:39], v[176:177], v[32:33] op_sel_hi:[1,0]
	v_pk_mul_f32 v[34:35], v[34:35], v[32:33] op_sel_hi:[1,0]
	s_waitcnt vmcnt(0)
	v_pk_mul_f32 v[36:37], v[28:29], v[36:37]
	v_pk_mul_f32 v[38:39], v[30:31], v[38:39]
	v_pk_mul_f32 v[34:35], v[24:25], v[34:35]
	v_cvt_pk_bf16_f32 v36, v36, v37
	v_cvt_pk_bf16_f32 v37, v38, v39
	v_cvt_pk_bf16_f32 v38, v34, v35
	v_pk_mul_f32 v[34:35], v[172:173], v[32:33] op_sel_hi:[1,0]
	v_lshlrev_b32_e32 v33, 8, v239
	v_pk_mul_f32 v[34:35], v[26:27], v[34:35]
	v_and_b32_e32 v212, 0x3800, v33
	v_cvt_pk_bf16_f32 v39, v34, v35
	v_lshl_add_u64 v[34:35], v[72:73], 0, v[212:213]
	global_store_dwordx4 v[34:35], v[36:39], off
	v_lshlrev_b32_e32 v172, 16, v16
	v_and_b32_e32 v173, 0xffff0000, v16
	v_lshlrev_b32_e32 v36, 16, v19
	v_and_b32_e32 v37, 0xffff0000, v19
	v_and_b32_e32 v19, 0xffff0000, v22
	v_lshlrev_b32_e32 v38, 16, v23
	v_and_b32_e32 v39, 0xffff0000, v23
	v_pk_fma_f32 v[18:19], s[10:11], v[18:19], v[86:87] neg_lo:[1,0,0] neg_hi:[1,0,0]
	v_lshlrev_b32_e32 v86, 16, v17
	v_and_b32_e32 v87, 0xffff0000, v17
	v_lshlrev_b32_e32 v16, 16, v20
	v_and_b32_e32 v17, 0xffff0000, v20
	v_pk_fma_f32 v[36:37], s[10:11], v[38:39], v[36:37] neg_lo:[1,0,0] neg_hi:[1,0,0]
	v_pk_fma_f32 v[86:87], s[10:11], v[88:89], v[86:87] neg_lo:[1,0,0] neg_hi:[1,0,0]
	v_pk_fma_f32 v[20:21], s[10:11], v[16:17], v[172:173] neg_lo:[1,0,0] neg_hi:[1,0,0]
	v_pk_mul_f32 v[38:39], v[36:37], v[36:37]
	v_pk_mul_f32 v[88:89], v[86:87], v[86:87]
	v_pk_mul_f32 v[16:17], v[20:21], v[20:21]
	v_pk_mul_f32 v[22:23], v[18:19], v[18:19]
	v_add_f32_e32 v33, v38, v39
	v_add_f32_e32 v38, v88, v89
	v_add_f32_e32 v16, v16, v17
	v_add_f32_e32 v16, v16, v38
	v_add_f32_e32 v17, v22, v23
	v_add_f32_e32 v16, v17, v16
	v_add_f32_e32 v16, v33, v16
	v_add_f32_e32 v16, v16, v82
	v_add_f32_e32 v16, v83, v16
	v_add_f32_e32 v16, v84, v16
	v_add_f32_e32 v16, v85, v16
	ds_bpermute_b32 v17, v171, v16
	v_lshlrev_b32_e32 v38, 16, v13
	v_and_b32_e32 v39, 0xffff0000, v13
	v_lshlrev_b32_e32 v82, 16, v8
	v_and_b32_e32 v83, 0xffff0000, v8
	s_waitcnt lgkmcnt(0)
	v_add_f32_e32 v16, v16, v17
	ds_bpermute_b32 v17, v170, v16
	v_lshlrev_b32_e32 v8, 16, v12
	s_waitcnt lgkmcnt(0)
	v_add_f32_e32 v16, v16, v17
	ds_bpermute_b32 v17, v169, v16
	s_waitcnt lgkmcnt(0)
	v_add_f32_e32 v16, v16, v17
	v_fmamk_f32 v16, v16, 0x3c000000, v251
	v_rsq_f32_e32 v16, v16
	s_nop 0
	v_mul_f32_e32 v16, v238, v16
	v_pk_mul_f32 v[20:21], v[20:21], v[16:17] op_sel_hi:[1,0]
	v_pk_mul_f32 v[22:23], v[86:87], v[16:17] op_sel_hi:[1,0]
	v_pk_mul_f32 v[18:19], v[18:19], v[16:17] op_sel_hi:[1,0]
	v_pk_mul_f32 v[20:21], v[28:29], v[20:21]
	v_pk_mul_f32 v[22:23], v[30:31], v[22:23]
	v_pk_mul_f32 v[18:19], v[24:25], v[18:19]
	v_cvt_pk_bf16_f32 v20, v20, v21
	v_cvt_pk_bf16_f32 v21, v22, v23
	v_cvt_pk_bf16_f32 v22, v18, v19
	v_pk_mul_f32 v[18:19], v[36:37], v[16:17] op_sel_hi:[1,0]
	s_nop 0
	v_pk_mul_f32 v[18:19], v[26:27], v[18:19]
	s_nop 0
	v_cvt_pk_bf16_f32 v23, v18, v19
	v_or_b32_e32 v18, 0x4000, v212
	v_mov_b32_e32 v19, v213
	v_lshl_add_u64 v[36:37], v[72:73], 0, v[18:19]
	global_store_dwordx4 v[36:37], v[20:23], off
	v_lshlrev_b32_e32 v36, 16, v10
	v_and_b32_e32 v37, 0xffff0000, v10
	v_lshlrev_b32_e32 v20, 16, v11
	v_and_b32_e32 v21, 0xffff0000, v11
	v_lshlrev_b32_e32 v10, 16, v14
	v_and_b32_e32 v11, 0xffff0000, v14
	v_lshlrev_b32_e32 v22, 16, v15
	v_and_b32_e32 v23, 0xffff0000, v15
	v_pk_fma_f32 v[10:11], s[10:11], v[10:11], v[36:37] neg_lo:[1,0,0] neg_hi:[1,0,0]
	v_lshlrev_b32_e32 v36, 16, v9
	v_and_b32_e32 v37, 0xffff0000, v9
	v_and_b32_e32 v9, 0xffff0000, v12
	v_pk_fma_f32 v[20:21], s[10:11], v[22:23], v[20:21] neg_lo:[1,0,0] neg_hi:[1,0,0]
	v_pk_fma_f32 v[36:37], s[10:11], v[38:39], v[36:37] neg_lo:[1,0,0] neg_hi:[1,0,0]
	v_pk_fma_f32 v[12:13], s[10:11], v[8:9], v[82:83] neg_lo:[1,0,0] neg_hi:[1,0,0]
	v_pk_mul_f32 v[22:23], v[20:21], v[20:21]
	v_pk_mul_f32 v[38:39], v[36:37], v[36:37]
	v_pk_mul_f32 v[8:9], v[12:13], v[12:13]
	v_pk_mul_f32 v[14:15], v[10:11], v[10:11]
	v_add_f32_e32 v17, v22, v23
	v_add_f32_e32 v22, v38, v39
	v_add_f32_e32 v8, v8, v9
	v_add_f32_e32 v8, v8, v22
	v_add_f32_e32 v9, v14, v15
	v_add_f32_e32 v8, v9, v8
	v_add_f32_e32 v8, v17, v8
	v_add_f32_e32 v8, v8, v78
	v_add_f32_e32 v8, v79, v8
	v_add_f32_e32 v8, v80, v8
	v_add_f32_e32 v8, v81, v8
	ds_bpermute_b32 v9, v171, v8
	v_lshlrev_b32_e32 v22, 16, v5
	v_and_b32_e32 v23, 0xffff0000, v5
	s_waitcnt lgkmcnt(0)
	v_add_f32_e32 v8, v8, v9
	ds_bpermute_b32 v9, v170, v8
	s_waitcnt lgkmcnt(0)
	v_add_f32_e32 v8, v8, v9
	ds_bpermute_b32 v9, v169, v8
	s_waitcnt lgkmcnt(0)
	v_add_f32_e32 v8, v8, v9
	v_fmamk_f32 v8, v8, 0x3c000000, v251
	v_rsq_f32_e32 v8, v8
	s_nop 0
	v_mul_f32_e32 v8, v238, v8
	v_pk_mul_f32 v[12:13], v[12:13], v[8:9] op_sel_hi:[1,0]
	v_pk_mul_f32 v[14:15], v[36:37], v[8:9] op_sel_hi:[1,0]
	v_pk_mul_f32 v[10:11], v[10:11], v[8:9] op_sel_hi:[1,0]
	v_pk_mul_f32 v[12:13], v[28:29], v[12:13]
	v_pk_mul_f32 v[14:15], v[30:31], v[14:15]
	v_pk_mul_f32 v[10:11], v[24:25], v[10:11]
	v_cvt_pk_bf16_f32 v12, v12, v13
	v_cvt_pk_bf16_f32 v13, v14, v15
	v_cvt_pk_bf16_f32 v14, v10, v11
	v_pk_mul_f32 v[10:11], v[20:21], v[8:9] op_sel_hi:[1,0]
	v_lshlrev_b32_e32 v36, 16, v0
	v_pk_mul_f32 v[10:11], v[26:27], v[10:11]
	v_and_b32_e32 v37, 0xffff0000, v0
	v_cvt_pk_bf16_f32 v15, v10, v11
	v_or_b32_e32 v10, 0x8000, v212
	v_mov_b32_e32 v11, v213
	v_lshl_add_u64 v[20:21], v[72:73], 0, v[10:11]
	global_store_dwordx4 v[20:21], v[12:15], off
	v_lshlrev_b32_e32 v20, 16, v2
	v_and_b32_e32 v21, 0xffff0000, v2
	v_lshlrev_b32_e32 v12, 16, v3
	v_and_b32_e32 v13, 0xffff0000, v3
	v_lshlrev_b32_e32 v2, 16, v6
	v_and_b32_e32 v3, 0xffff0000, v6
	v_lshlrev_b32_e32 v14, 16, v7
	v_and_b32_e32 v15, 0xffff0000, v7
	v_pk_fma_f32 v[2:3], s[10:11], v[2:3], v[20:21] neg_lo:[1,0,0] neg_hi:[1,0,0]
	v_lshlrev_b32_e32 v20, 16, v1
	v_and_b32_e32 v21, 0xffff0000, v1
	v_lshlrev_b32_e32 v0, 16, v4
	v_and_b32_e32 v1, 0xffff0000, v4
	v_pk_fma_f32 v[12:13], s[10:11], v[14:15], v[12:13] neg_lo:[1,0,0] neg_hi:[1,0,0]
	v_pk_fma_f32 v[20:21], s[10:11], v[22:23], v[20:21] neg_lo:[1,0,0] neg_hi:[1,0,0]
	v_pk_fma_f32 v[0:1], s[10:11], v[0:1], v[36:37] neg_lo:[1,0,0] neg_hi:[1,0,0]
	v_pk_mul_f32 v[14:15], v[12:13], v[12:13]
	v_pk_mul_f32 v[22:23], v[20:21], v[20:21]
	v_pk_mul_f32 v[4:5], v[0:1], v[0:1]
	v_pk_mul_f32 v[6:7], v[2:3], v[2:3]
	v_add_f32_e32 v9, v14, v15
	v_add_f32_e32 v14, v22, v23
	v_add_f32_e32 v4, v4, v5
	v_add_f32_e32 v4, v4, v14
	v_add_f32_e32 v5, v6, v7
	v_add_f32_e32 v4, v5, v4
	v_add_f32_e32 v4, v9, v4
	v_add_f32_e32 v4, v4, v74
	v_add_f32_e32 v4, v75, v4
	v_add_f32_e32 v4, v76, v4
	v_add_f32_e32 v4, v77, v4
	ds_bpermute_b32 v5, v171, v4
	v_or_b32_e32 v212, 0xc000, v212
	s_waitcnt lgkmcnt(0)
	v_add_f32_e32 v4, v4, v5
	ds_bpermute_b32 v5, v170, v4
	s_waitcnt lgkmcnt(0)
	v_add_f32_e32 v4, v4, v5
	ds_bpermute_b32 v5, v169, v4
	s_waitcnt lgkmcnt(0)
	v_add_f32_e32 v4, v4, v5
	v_fmamk_f32 v4, v4, 0x3c000000, v251
	v_rsq_f32_e32 v4, v4
	s_nop 0
	v_mul_f32_e32 v22, v238, v4
	v_pk_mul_f32 v[0:1], v[0:1], v[22:23] op_sel_hi:[1,0]
	v_pk_mul_f32 v[4:5], v[20:21], v[22:23] op_sel_hi:[1,0]
	v_pk_mul_f32 v[0:1], v[28:29], v[0:1]
	v_pk_mul_f32 v[4:5], v[30:31], v[4:5]
	v_cvt_pk_bf16_f32 v0, v0, v1
	v_cvt_pk_bf16_f32 v1, v4, v5
	v_pk_mul_f32 v[2:3], v[2:3], v[22:23] op_sel_hi:[1,0]
	v_pk_mul_f32 v[4:5], v[12:13], v[22:23] op_sel_hi:[1,0]
	v_pk_mul_f32 v[2:3], v[24:25], v[2:3]
	v_pk_mul_f32 v[4:5], v[26:27], v[4:5]
	v_cvt_pk_bf16_f32 v2, v2, v3
	v_cvt_pk_bf16_f32 v3, v4, v5
	v_lshl_add_u64 v[4:5], v[72:73], 0, v[212:213]
	global_store_dwordx4 v[4:5], v[0:3], off
	v_mov_b64_e32 v[4:5], v[204:205]
	v_mov_b64_e32 v[6:7], v[206:207]
	v_mov_b64_e32 v[0:1], v[200:201]
	v_mov_b64_e32 v[2:3], v[202:203]
	v_mov_b32_e32 v12, v50
	v_mov_b32_e32 v13, v48
	v_mov_b32_e32 v48, v51
	v_pk_mul_f32 v[12:13], v[12:13], v[32:33] op_sel_hi:[1,0]
	v_pk_mul_f32 v[14:15], v[48:49], v[32:33] op_sel_hi:[1,0]
	v_lshl_add_u64 v[20:21], v[72:73], 0, s[44:45]
	v_pk_mul_f32 v[12:13], v[12:13], v[4:5]
	v_pk_mul_f32 v[14:15], v[14:15], v[6:7]
	v_cvt_pk_bf16_f32 v12, v12, v13
	v_cvt_pk_bf16_f32 v13, v14, v15
	v_mov_b32_e32 v14, v46
	v_mov_b32_e32 v15, v44
	v_mov_b32_e32 v44, v47
	v_pk_mul_f32 v[14:15], v[14:15], v[32:33] op_sel_hi:[1,0]
	v_pk_mul_f32 v[24:25], v[44:45], v[32:33] op_sel_hi:[1,0]
	v_pk_mul_f32 v[14:15], v[14:15], v[0:1]
	v_pk_mul_f32 v[24:25], v[24:25], v[2:3]
	v_cvt_pk_bf16_f32 v14, v14, v15
	v_cvt_pk_bf16_f32 v15, v24, v25
	global_store_dwordx4 v[34:35], v[12:15], off offset:128
	s_nop 1
	v_mov_b32_e32 v12, v52
	v_mov_b32_e32 v13, v40
	v_mov_b32_e32 v40, v53
	v_pk_mul_f32 v[12:13], v[12:13], v[16:17] op_sel_hi:[1,0]
	v_pk_mul_f32 v[14:15], v[40:41], v[16:17] op_sel_hi:[1,0]
	v_pk_mul_f32 v[12:13], v[12:13], v[4:5]
	v_pk_mul_f32 v[14:15], v[14:15], v[6:7]
	v_cvt_pk_bf16_f32 v12, v12, v13
	v_cvt_pk_bf16_f32 v13, v14, v15
	v_mov_b32_e32 v14, v62
	v_mov_b32_e32 v15, v60
	v_mov_b32_e32 v60, v63
	v_pk_mul_f32 v[14:15], v[14:15], v[16:17] op_sel_hi:[1,0]
	v_pk_mul_f32 v[16:17], v[60:61], v[16:17] op_sel_hi:[1,0]
	v_pk_mul_f32 v[14:15], v[14:15], v[0:1]
	v_pk_mul_f32 v[16:17], v[16:17], v[2:3]
	v_cvt_pk_bf16_f32 v14, v14, v15
	v_cvt_pk_bf16_f32 v15, v16, v17
	v_lshl_add_u64 v[16:17], v[20:21], 0, v[18:19]
	global_store_dwordx4 v[16:17], v[12:15], off
	s_nop 1
	v_mov_b32_e32 v12, v56
	v_mov_b32_e32 v13, v54
	v_mov_b32_e32 v54, v57
	v_pk_mul_f32 v[12:13], v[12:13], v[8:9] op_sel_hi:[1,0]
	v_pk_mul_f32 v[14:15], v[54:55], v[8:9] op_sel_hi:[1,0]
	v_pk_mul_f32 v[12:13], v[12:13], v[4:5]
	v_pk_mul_f32 v[14:15], v[14:15], v[6:7]
	v_cvt_pk_bf16_f32 v12, v12, v13
	v_cvt_pk_bf16_f32 v13, v14, v15
	v_mov_b32_e32 v14, v58
	v_mov_b32_e32 v15, v42
	v_mov_b32_e32 v42, v59
	v_pk_mul_f32 v[14:15], v[14:15], v[8:9] op_sel_hi:[1,0]
	v_pk_mul_f32 v[8:9], v[42:43], v[8:9] op_sel_hi:[1,0]
	v_pk_mul_f32 v[14:15], v[14:15], v[0:1]
	v_pk_mul_f32 v[8:9], v[8:9], v[2:3]
	v_cvt_pk_bf16_f32 v14, v14, v15
	v_cvt_pk_bf16_f32 v15, v8, v9
	v_lshl_add_u64 v[8:9], v[20:21], 0, v[10:11]
	global_store_dwordx4 v[8:9], v[12:15], off
	v_mov_b32_e32 v8, v66
	v_mov_b32_e32 v9, v64
	v_pk_mul_f32 v[8:9], v[8:9], v[22:23] op_sel_hi:[1,0]
	v_mov_b32_e32 v64, v67
	v_pk_mul_f32 v[4:5], v[8:9], v[4:5]
	v_pk_mul_f32 v[8:9], v[64:65], v[22:23] op_sel_hi:[1,0]
	v_cvt_pk_bf16_f32 v4, v4, v5
	v_pk_mul_f32 v[6:7], v[8:9], v[6:7]
	s_nop 0
	v_cvt_pk_bf16_f32 v5, v6, v7
	v_mov_b32_e32 v6, v70
	v_mov_b32_e32 v7, v68
	v_pk_mul_f32 v[6:7], v[6:7], v[22:23] op_sel_hi:[1,0]
	v_mov_b32_e32 v68, v71
	v_pk_mul_f32 v[0:1], v[6:7], v[0:1]
	s_nop 0
	v_cvt_pk_bf16_f32 v6, v0, v1
	v_pk_mul_f32 v[0:1], v[68:69], v[22:23] op_sel_hi:[1,0]
	s_nop 0
	v_pk_mul_f32 v[0:1], v[0:1], v[2:3]
	s_nop 0
	v_cvt_pk_bf16_f32 v7, v0, v1
	v_lshl_add_u64 v[0:1], v[20:21], 0, v[212:213]
	global_store_dwordx4 v[0:1], v[4:7], off

.LBB0_813:
	s_or_b64 exec, exec, s[8:9]
	v_lshlrev_b64 v[136:137], 10, v[156:157]
	v_pk_mul_f32 v[156:157], v[172:173], v[138:139] op_sel_hi:[1,0]
	v_pk_mul_f32 v[172:173], v[176:177], v[138:139] op_sel_hi:[1,0]
	v_pk_fma_f32 v[156:157], v[120:121], v[156:157], v[112:113]
	v_pk_fma_f32 v[176:177], v[124:125], v[172:173], v[116:117]
	v_pk_mul_f32 v[170:171], v[170:171], v[138:139] op_sel_hi:[1,0]
	v_pk_mul_f32 v[172:173], v[174:175], v[138:139] op_sel_hi:[1,0]
	v_mul_f32_e32 v139, 4.0, v156
	v_mul_f32_e32 v175, 4.0, v157
	v_mov_b32_e32 v174, v213
	v_cvt_pk_fp8_f32 v174, v139, v175
	v_pk_fma_f32 v[178:179], v[122:123], v[170:171], v[114:115]
	v_mul_f32_e32 v182, 4.0, v177
	v_mul_f32_e32 v139, 4.0, v178
	v_mul_f32_e32 v175, 4.0, v179
	v_cvt_pk_fp8_f32 v174, v139, v175 op_sel:[0,0,1]
	v_mul_f32_e32 v139, 4.0, v176
	v_mov_b32_e32 v175, v213
	v_cvt_pk_fp8_f32 v175, v139, v182
	v_pk_fma_f32 v[180:181], v[126:127], v[172:173], v[118:119]
	v_lshl_add_u64 v[136:137], v[154:155], 0, v[136:137]
	v_mul_f32_e32 v139, 4.0, v180
	v_mul_f32_e32 v182, 4.0, v181
	v_cvt_pk_fp8_f32 v175, v139, v182 op_sel:[0,0,1]
	v_cvt_pk_bf16_f32 v170, v156, v157
	v_cvt_pk_bf16_f32 v171, v178, v179
	v_cvt_pk_bf16_f32 v172, v176, v177
	global_store_dwordx2 v[136:137], v[174:175], off
	v_lshlrev_b32_e32 v174, 16, v170
	v_and_b32_e32 v175, 0xffff0000, v170
	v_pk_add_f32 v[156:157], v[156:157], v[174:175] neg_lo:[0,1] neg_hi:[0,1]
	v_cvt_pk_bf16_f32 v173, v180, v181
	v_cvt_pk_bf16_f32 v174, v156, v157
	v_lshlrev_b32_e32 v156, 16, v171
	v_and_b32_e32 v157, 0xffff0000, v171
	v_pk_add_f32 v[156:157], v[178:179], v[156:157] neg_lo:[0,1] neg_hi:[0,1]
	v_mfma_f32_16x16x32_bf16 v[182:185], v[170:173], v[4:7], 0
	v_cvt_pk_bf16_f32 v175, v156, v157
	v_lshlrev_b32_e32 v156, 16, v172
	v_and_b32_e32 v157, 0xffff0000, v172
	v_pk_add_f32 v[156:157], v[176:177], v[156:157] neg_lo:[0,1] neg_hi:[0,1]
	v_pk_mul_f32 v[162:163], v[162:163], v[138:139] op_sel_hi:[1,0]
	v_cvt_pk_bf16_f32 v176, v156, v157
	v_lshlrev_b32_e32 v156, 16, v173
	v_and_b32_e32 v157, 0xffff0000, v173
	v_pk_add_f32 v[156:157], v[180:181], v[156:157] neg_lo:[0,1] neg_hi:[0,1]
	v_mfma_f32_16x16x32_bf16 v[178:181], v[170:173], v[8:11], 0
	v_cvt_pk_bf16_f32 v177, v156, v157
	v_pk_mul_f32 v[156:157], v[164:165], v[138:139] op_sel_hi:[1,0]
	v_pk_mul_f32 v[164:165], v[168:169], v[138:139] op_sel_hi:[1,0]
	v_mfma_f32_16x16x32_bf16 v[178:181], v[170:173], v[0:3], v[178:181]
	v_fma_f32 v156, v104, v156, v96
	v_fma_f32 v157, v105, v157, v97
	v_pk_fma_f32 v[168:169], v[108:109], v[164:165], v[100:101]
	v_pk_mul_f32 v[164:165], v[166:167], v[138:139] op_sel_hi:[1,0]
	v_mfma_f32_16x16x32_bf16 v[170:173], v[170:173], v[48:51], v[182:185]
	v_mul_f32_e32 v139, 4.0, v156
	v_mul_f32_e32 v167, 4.0, v157
	v_mov_b32_e32 v166, v213
	v_cvt_pk_fp8_f32 v166, v139, v167
	v_mfma_f32_16x16x32_bf16 v[178:181], v[174:177], v[8:11], v[178:181]
	v_mul_f32_e32 v182, 4.0, v169
	v_mfma_f32_16x16x32_bf16 v[170:173], v[174:177], v[4:7], v[170:173]
	v_fma_f32 v174, v106, v162, v98
	v_fma_f32 v175, v107, v163, v99
	v_pk_fma_f32 v[176:177], v[110:111], v[164:165], v[102:103]
	v_mul_f32_e32 v139, 4.0, v174
	v_mul_f32_e32 v167, 4.0, v175
	v_cvt_pk_fp8_f32 v166, v139, v167 op_sel:[0,0,1]
	v_mul_f32_e32 v139, 4.0, v168
	v_mov_b32_e32 v167, v213
	v_cvt_pk_fp8_f32 v167, v139, v182
	v_mul_f32_e32 v139, 4.0, v176
	v_mul_f32_e32 v182, 4.0, v177
	v_cvt_pk_bf16_f32 v162, v156, v157
	v_cvt_pk_fp8_f32 v167, v139, v182 op_sel:[0,0,1]
	v_cvt_pk_bf16_f32 v163, v174, v175
	v_cvt_pk_bf16_f32 v164, v168, v169
	v_cvt_pk_bf16_f32 v165, v176, v177
	global_store_dwordx2 v[136:137], v[166:167], off offset:32
	v_lshlrev_b32_e32 v166, 16, v162
	v_and_b32_e32 v167, 0xffff0000, v162
	v_pk_add_f32 v[156:157], v[156:157], v[166:167] neg_lo:[0,1] neg_hi:[0,1]
	v_mfma_f32_16x16x32_bf16 v[170:173], v[162:165], v[24:27], v[170:173]
	v_cvt_pk_bf16_f32 v166, v156, v157
	v_lshlrev_b32_e32 v156, 16, v163
	v_and_b32_e32 v157, 0xffff0000, v163
	v_pk_add_f32 v[156:157], v[174:175], v[156:157] neg_lo:[0,1] neg_hi:[0,1]
	v_pk_mul_f32 v[142:143], v[142:143], v[138:139] op_sel_hi:[1,0]
	v_cvt_pk_bf16_f32 v167, v156, v157
	v_lshlrev_b32_e32 v156, 16, v164
	v_and_b32_e32 v157, 0xffff0000, v164
	v_pk_add_f32 v[156:157], v[168:169], v[156:157] neg_lo:[0,1] neg_hi:[0,1]
	v_pk_mul_f32 v[140:141], v[140:141], v[138:139] op_sel_hi:[1,0]
	v_cvt_pk_bf16_f32 v168, v156, v157
	v_lshlrev_b32_e32 v156, 16, v165
	v_and_b32_e32 v157, 0xffff0000, v165
	v_pk_add_f32 v[156:157], v[176:177], v[156:157] neg_lo:[0,1] neg_hi:[0,1]
	v_mfma_f32_16x16x32_bf16 v[174:177], v[162:165], v[12:15], v[178:181]
	v_cvt_pk_bf16_f32 v169, v156, v157
	v_pk_mul_f32 v[156:157], v[160:161], v[138:139] op_sel_hi:[1,0]
	v_pk_fma_f32 v[160:161], v[88:89], v[142:143], v[80:81]
	v_mfma_f32_16x16x32_bf16 v[174:177], v[162:165], v[16:19], v[174:177]
	v_mul_f32_e64 v142, v158, v138
	v_mul_f32_e64 v143, v159, v138
	v_mul_f32_e32 v139, 4.0, v160
	v_pk_fma_f32 v[158:159], v[90:91], v[140:141], v[82:83]
	v_mfma_f32_16x16x32_bf16 v[162:165], v[162:165], v[20:23], v[170:173]
	v_cvt_pk_bf16_f32 v140, v160, v161
	v_cvt_pk_bf16_f32 v141, v158, v159
	v_mfma_f32_16x16x32_bf16 v[174:177], v[166:169], v[12:15], v[174:177]
	v_mfma_f32_16x16x32_bf16 v[162:165], v[166:169], v[24:27], v[162:165]
	v_fma_f32 v166, v92, v156, v84
	v_fma_f32 v167, v93, v157, v85
	v_mul_f32_e32 v157, 4.0, v161
	v_mov_b32_e32 v156, v213
	v_cvt_pk_fp8_f32 v156, v139, v157
	v_mul_f32_e32 v139, 4.0, v158
	v_mul_f32_e32 v157, 4.0, v159
	v_mul_f32_e32 v170, 4.0, v167
	v_cvt_pk_fp8_f32 v156, v139, v157 op_sel:[0,0,1]
	v_mul_f32_e32 v139, 4.0, v166
	v_mov_b32_e32 v157, v213
	v_cvt_pk_fp8_f32 v157, v139, v170
	v_pk_fma_f32 v[168:169], v[94:95], v[142:143], v[86:87]
	v_cvt_pk_bf16_f32 v142, v166, v167
	v_mul_f32_e32 v139, 4.0, v168
	v_mul_f32_e32 v170, 4.0, v169
	v_cvt_pk_fp8_f32 v157, v139, v170 op_sel:[0,0,1]
	v_cvt_pk_bf16_f32 v143, v168, v169
	v_pk_mul_f32 v[130:131], v[130:131], v[138:139] op_sel_hi:[1,0]
	v_pk_mul_f32 v[128:129], v[128:129], v[138:139] op_sel_hi:[1,0]
	global_store_dwordx2 v[136:137], v[156:157], off offset:64
	v_lshlrev_b32_e32 v156, 16, v140
	v_and_b32_e32 v157, 0xffff0000, v140
	v_pk_add_f32 v[156:157], v[160:161], v[156:157] neg_lo:[0,1] neg_hi:[0,1]
	v_lshlrev_b32_e32 v160, 16, v141
	v_and_b32_e32 v161, 0xffff0000, v141
	v_pk_add_f32 v[158:159], v[158:159], v[160:161] neg_lo:[0,1] neg_hi:[0,1]
	v_cvt_pk_bf16_f32 v156, v156, v157
	v_cvt_pk_bf16_f32 v157, v158, v159
	v_lshlrev_b32_e32 v158, 16, v142
	v_and_b32_e32 v159, 0xffff0000, v142
	v_lshlrev_b32_e32 v160, 16, v143
	v_and_b32_e32 v161, 0xffff0000, v143
	v_pk_add_f32 v[158:159], v[166:167], v[158:159] neg_lo:[0,1] neg_hi:[0,1]
	v_pk_add_f32 v[160:161], v[168:169], v[160:161] neg_lo:[0,1] neg_hi:[0,1]
	v_cvt_pk_bf16_f32 v158, v158, v159
	v_cvt_pk_bf16_f32 v159, v160, v161
	v_mfma_f32_16x16x32_bf16 v[166:169], v[140:143], v[40:43], v[174:177]
	v_mul_f32_e64 v134, v134, v138
	v_mul_f32_e64 v135, v135, v138
	v_pk_fma_f32 v[134:135], v[76:77], v[134:135], v[68:69]
	v_mfma_f32_16x16x32_bf16 v[160:163], v[140:143], v[28:31], v[162:165]
	v_mfma_f32_16x16x32_bf16 v[166:169], v[140:143], v[32:35], v[166:169]
	v_mfma_f32_16x16x32_bf16 v[140:143], v[140:143], v[36:39], v[160:163]
	v_mfma_f32_16x16x32_bf16 v[166:169], v[156:159], v[40:43], v[166:169]
	s_nop 4
	v_mul_f32_e32 v161, 4.0, v135
	v_mfma_f32_16x16x32_bf16 v[140:143], v[156:159], v[28:31], v[140:143]
	v_fma_f32 v156, v72, v130, v64
	v_fma_f32 v157, v73, v131, v65
	v_pk_mul_f32 v[130:131], v[132:133], v[138:139] op_sel_hi:[1,0]
	v_mul_f32_e32 v133, 4.0, v156
	v_mul_f32_e32 v160, 4.0, v157
	v_mov_b32_e32 v132, v213
	v_cvt_pk_fp8_f32 v132, v133, v160
	v_pk_fma_f32 v[138:139], v[74:75], v[128:129], v[66:67]
	v_pk_fma_f32 v[158:159], v[78:79], v[130:131], v[70:71]
	v_mul_f32_e32 v133, 4.0, v138
	v_mul_f32_e32 v160, 4.0, v139
	v_cvt_pk_fp8_f32 v132, v133, v160 op_sel:[0,0,1]
	v_mul_f32_e32 v160, 4.0, v134
	v_mov_b32_e32 v133, v213
	v_cvt_pk_fp8_f32 v133, v160, v161
	v_mul_f32_e32 v160, 4.0, v158
	v_mul_f32_e32 v161, 4.0, v159
	v_cvt_pk_bf16_f32 v128, v156, v157
	v_cvt_pk_fp8_f32 v133, v160, v161 op_sel:[0,0,1]
	v_cvt_pk_bf16_f32 v129, v138, v139
	v_cvt_pk_bf16_f32 v130, v134, v135
	v_cvt_pk_bf16_f32 v131, v158, v159
	global_store_dwordx2 v[136:137], v[132:133], off offset:96
	v_lshlrev_b32_e32 v132, 16, v128
	v_and_b32_e32 v133, 0xffff0000, v128
	v_lshlrev_b32_e32 v136, 16, v129
	v_and_b32_e32 v137, 0xffff0000, v129
	v_pk_add_f32 v[132:133], v[156:157], v[132:133] neg_lo:[0,1] neg_hi:[0,1]
	v_pk_add_f32 v[136:137], v[138:139], v[136:137] neg_lo:[0,1] neg_hi:[0,1]
	v_cvt_pk_bf16_f32 v132, v132, v133
	v_cvt_pk_bf16_f32 v133, v136, v137
	v_lshlrev_b32_e32 v136, 16, v130
	v_and_b32_e32 v137, 0xffff0000, v130
	v_pk_add_f32 v[134:135], v[134:135], v[136:137] neg_lo:[0,1] neg_hi:[0,1]
	v_lshlrev_b32_e32 v136, 16, v131
	v_and_b32_e32 v137, 0xffff0000, v131
	v_pk_add_f32 v[136:137], v[158:159], v[136:137] neg_lo:[0,1] neg_hi:[0,1]
	v_cvt_pk_bf16_f32 v134, v134, v135
	v_cvt_pk_bf16_f32 v135, v136, v137
	v_mfma_f32_16x16x32_bf16 v[136:139], v[128:131], v[44:47], v[166:169]
	v_mfma_f32_16x16x32_bf16 v[140:143], v[128:131], v[52:55], v[140:143]
	v_mfma_f32_16x16x32_bf16 v[136:139], v[128:131], v[56:59], v[136:139]
	v_mfma_f32_16x16x32_bf16 v[128:131], v[128:131], v[60:63], v[140:143]
	v_mfma_f32_16x16x32_bf16 v[136:139], v[132:135], v[44:47], v[136:139]
	v_mfma_f32_16x16x32_bf16 v[128:131], v[132:135], v[52:55], v[128:131]
	s_nop 7
	ds_write2_b32 v188, v136, v128 offset1:16
	ds_write2_b32 v188, v137, v129 offset0:32 offset1:48
	ds_write2_b32 v188, v138, v130 offset0:64 offset1:80
	ds_write2_b32 v188, v139, v131 offset0:96 offset1:112
	s_waitcnt lgkmcnt(0)
	s_barrier
	ds_read2st64_b32 v[128:129], v216 offset0:4 offset1:12
	ds_read2st64_b32 v[244:245], v216 offset0:20 offset1:28
	ds_read2st64_b32 v[246:247], v216 offset0:36 offset1:44
	ds_read2st64_b32 v[248:249], v216 offset0:52 offset1:60
	s_waitcnt lgkmcnt(3)
	v_add_f32_e32 v128, v253, v128
	v_add_f32_e32 v130, v128, v129
	s_waitcnt lgkmcnt(2)
	v_add_f32_e32 v128, v130, v244
	v_add_f32_e32 v130, v128, v245
	s_waitcnt lgkmcnt(1)
	v_add_f32_e32 v128, v130, v246
	v_add_f32_e32 v130, v128, v247
	s_waitcnt lgkmcnt(0)
	v_add_f32_e32 v128, v130, v248
	v_add_f32_e32 v128, v128, v249
	v_add_u32_e32 v129, v215, v219
	ds_write_b32 v129, v128 offset:32192
	s_waitcnt lgkmcnt(0)
	s_barrier
	s_and_saveexec_b64 s[8:9], s[6:7]
	s_cbranch_execz .LBB0_815
	v_add_u32_e32 v128, 0x4400, v221
	v_add_u32_e32 v134, 0x4410, v221
	v_add_u32_e32 v136, 0x4418, v221
	v_add_u32_e32 v129, 0x4408, v221
	ds_read2_b32 v[130:131], v128 offset1:1
	ds_read2_b32 v[132:133], v129 offset1:1
	ds_read2_b32 v[134:135], v134 offset1:1
	ds_read2_b32 v[136:137], v136 offset1:1
	v_add_u32_e32 v128, 0x4420, v221
	v_add_u32_e32 v142, 0x4430, v221
	v_add_u32_e32 v156, 0x4438, v221
	v_add_u32_e32 v129, 0x4428, v221
	ds_read2_b32 v[138:139], v128 offset1:1
	ds_read2_b32 v[140:141], v129 offset1:1
	ds_read2_b32 v[142:143], v142 offset1:1
	ds_read2_b32 v[156:157], v156 offset1:1
	v_add_u32_e32 v128, 0x4440, v221
	v_add_u32_e32 v162, 0x4450, v221
	v_add_u32_e32 v164, 0x4458, v221
	v_add_u32_e32 v129, 0x4448, v221
	ds_read2_b32 v[158:159], v128 offset1:1
	ds_read2_b32 v[160:161], v129 offset1:1
	ds_read2_b32 v[162:163], v162 offset1:1
	ds_read2_b32 v[164:165], v164 offset1:1
	v_add_u32_e32 v128, 0x4460, v221
	v_add_u32_e32 v170, 0x4470, v221
	v_add_u32_e32 v172, 0x4478, v221
	v_add_u32_e32 v129, 0x4468, v221
	ds_read2_b32 v[166:167], v128 offset1:1
	ds_read2_b32 v[168:169], v129 offset1:1
	ds_read2_b32 v[170:171], v170 offset1:1
	ds_read2_b32 v[172:173], v172 offset1:1
	s_waitcnt lgkmcnt(14)
	v_max_f32_e32 v128, v130, v130
	v_max_f32_e32 v128, 0xff800000, v128
	v_cmp_gt_f32_e32 vcc, v131, v128
	s_nop 1
	v_cndmask_b32_e32 v128, v128, v131, vcc
	v_cndmask_b32_e64 v129, 0, 1, vcc
	v_cmp_gt_f32_e32 vcc, v132, v128
	s_nop 1
	v_cndmask_b32_e32 v128, v128, v132, vcc
	v_cndmask_b32_e64 v129, v129, 2, vcc
	v_cmp_gt_f32_e32 vcc, v133, v128
	s_nop 1
	v_cndmask_b32_e32 v128, v128, v133, vcc
	v_cndmask_b32_e64 v129, v129, 3, vcc
	s_waitcnt lgkmcnt(13)
	v_cmp_gt_f32_e32 vcc, v134, v128
	s_nop 1
	v_cndmask_b32_e32 v128, v128, v134, vcc
	v_cndmask_b32_e64 v129, v129, 4, vcc
	v_cmp_gt_f32_e32 vcc, v135, v128
	s_nop 1
	v_cndmask_b32_e32 v128, v128, v135, vcc
	v_cndmask_b32_e64 v129, v129, 5, vcc
	s_waitcnt lgkmcnt(12)
	v_cmp_gt_f32_e32 vcc, v136, v128
	s_nop 1
	v_cndmask_b32_e32 v128, v128, v136, vcc
	v_cndmask_b32_e64 v129, v129, 6, vcc
	v_cmp_gt_f32_e32 vcc, v137, v128
	s_nop 1
	v_cndmask_b32_e32 v128, v128, v137, vcc
	v_cndmask_b32_e64 v129, v129, 7, vcc
	s_waitcnt lgkmcnt(11)
	v_cmp_gt_f32_e32 vcc, v138, v128
	s_nop 1
	v_cndmask_b32_e32 v128, v128, v138, vcc
	v_cndmask_b32_e64 v129, v129, 8, vcc
	v_cmp_gt_f32_e32 vcc, v139, v128
	s_nop 1
	v_cndmask_b32_e32 v128, v128, v139, vcc
	v_cndmask_b32_e64 v129, v129, 9, vcc
	s_waitcnt lgkmcnt(10)
	v_cmp_gt_f32_e32 vcc, v140, v128
	s_nop 1
	v_cndmask_b32_e32 v128, v128, v140, vcc
	v_cndmask_b32_e64 v129, v129, 10, vcc
	v_cmp_gt_f32_e32 vcc, v141, v128
	s_nop 1
	v_cndmask_b32_e32 v128, v128, v141, vcc
	v_cndmask_b32_e64 v129, v129, 11, vcc
	s_waitcnt lgkmcnt(9)
	v_cmp_gt_f32_e32 vcc, v142, v128
	s_nop 1
	v_cndmask_b32_e32 v128, v128, v142, vcc
	v_cndmask_b32_e64 v129, v129, 12, vcc
	v_cmp_gt_f32_e32 vcc, v143, v128
	s_nop 1
	v_cndmask_b32_e32 v128, v128, v143, vcc
	v_cndmask_b32_e64 v129, v129, 13, vcc
	s_waitcnt lgkmcnt(8)
	v_cmp_gt_f32_e32 vcc, v156, v128
	s_nop 1
	v_cndmask_b32_e32 v128, v128, v156, vcc
	v_cndmask_b32_e64 v129, v129, 14, vcc
	v_cmp_gt_f32_e32 vcc, v157, v128
	s_nop 1
	v_cndmask_b32_e32 v128, v128, v157, vcc
	v_cndmask_b32_e64 v129, v129, 15, vcc
	s_waitcnt lgkmcnt(7)
	v_cmp_gt_f32_e32 vcc, v158, v128
	s_nop 1
	v_cndmask_b32_e32 v128, v128, v158, vcc
	v_cndmask_b32_e64 v129, v129, 16, vcc
	v_cmp_gt_f32_e32 vcc, v159, v128
	s_nop 1
	v_cndmask_b32_e32 v128, v128, v159, vcc
	v_cndmask_b32_e64 v129, v129, 17, vcc
	s_waitcnt lgkmcnt(6)
	v_cmp_gt_f32_e32 vcc, v160, v128
	s_nop 1
	v_cndmask_b32_e32 v128, v128, v160, vcc
	v_cndmask_b32_e64 v129, v129, 18, vcc
	v_cmp_gt_f32_e32 vcc, v161, v128
	s_nop 1
	v_cndmask_b32_e32 v128, v128, v161, vcc
	v_cndmask_b32_e64 v129, v129, 19, vcc
	s_waitcnt lgkmcnt(5)
	v_cmp_gt_f32_e32 vcc, v162, v128
	s_nop 1
	v_cndmask_b32_e32 v128, v128, v162, vcc
	v_cndmask_b32_e64 v129, v129, 20, vcc
	v_cmp_gt_f32_e32 vcc, v163, v128
	s_nop 1
	v_cndmask_b32_e32 v128, v128, v163, vcc
	v_cndmask_b32_e64 v129, v129, 21, vcc
	s_waitcnt lgkmcnt(4)
	v_cmp_gt_f32_e32 vcc, v164, v128
	s_nop 1
	v_cndmask_b32_e32 v128, v128, v164, vcc
	v_cndmask_b32_e64 v129, v129, 22, vcc
	v_cmp_gt_f32_e32 vcc, v165, v128
	s_nop 1
	v_cndmask_b32_e32 v128, v128, v165, vcc
	v_cndmask_b32_e64 v129, v129, 23, vcc
	s_waitcnt lgkmcnt(3)
	v_cmp_gt_f32_e32 vcc, v166, v128
	s_nop 1
	v_cndmask_b32_e32 v128, v128, v166, vcc
	v_cndmask_b32_e64 v129, v129, 24, vcc
	v_cmp_gt_f32_e32 vcc, v167, v128
	s_nop 1
	v_cndmask_b32_e32 v128, v128, v167, vcc
	v_cndmask_b32_e64 v129, v129, 25, vcc
	s_waitcnt lgkmcnt(2)
	v_cmp_gt_f32_e32 vcc, v168, v128
	s_nop 1
	v_cndmask_b32_e32 v128, v128, v168, vcc
	v_cndmask_b32_e64 v129, v129, 26, vcc
	v_cmp_gt_f32_e32 vcc, v169, v128
	s_nop 1
	v_cndmask_b32_e32 v128, v128, v169, vcc
	v_cndmask_b32_e64 v129, v129, 27, vcc
	s_waitcnt lgkmcnt(1)
	v_cmp_gt_f32_e32 vcc, v170, v128
	s_nop 1
	v_cndmask_b32_e32 v128, v128, v170, vcc
	v_cndmask_b32_e64 v129, v129, 28, vcc
	v_cmp_gt_f32_e32 vcc, v171, v128
	s_nop 1
	v_cndmask_b32_e32 v128, v128, v171, vcc
	v_cndmask_b32_e64 v129, v129, 29, vcc
	s_waitcnt lgkmcnt(0)
	v_cmp_gt_f32_e32 vcc, v172, v128
	s_nop 1
	v_cndmask_b32_e32 v174, v128, v172, vcc
	v_cndmask_b32_e64 v129, v129, 30, vcc
	v_cmp_gt_f32_e32 vcc, v173, v174
	s_nop 1
	v_cndmask_b32_e64 v128, v129, 31, vcc
	v_cndmask_b32_e32 v174, v174, v173, vcc
	v_cmp_ne_u32_e32 vcc, 0, v128
	s_nop 1
	v_cndmask_b32_e32 v130, v233, v130, vcc
	v_cmp_ne_u32_e32 vcc, 1, v128
	v_max_f32_e32 v129, v130, v130
	v_max_f32_e32 v129, 0xff800000, v129
	v_cndmask_b32_e32 v131, v233, v131, vcc
	v_cmp_ne_u32_e32 vcc, 2, v128
	s_nop 1
	v_cndmask_b32_e32 v132, v233, v132, vcc
	v_cmp_ne_u32_e32 vcc, 3, v128
	s_nop 1
	v_cndmask_b32_e32 v133, v233, v133, vcc
	v_cmp_ne_u32_e32 vcc, 4, v128
	s_nop 1
	v_cndmask_b32_e32 v134, v233, v134, vcc
	v_cmp_ne_u32_e32 vcc, 5, v128
	s_nop 1
	v_cndmask_b32_e32 v135, v233, v135, vcc
	v_cmp_ne_u32_e32 vcc, 6, v128
	s_nop 1
	v_cndmask_b32_e32 v136, v233, v136, vcc
	v_cmp_ne_u32_e32 vcc, 7, v128
	s_nop 1
	v_cndmask_b32_e32 v137, v233, v137, vcc
	v_cmp_ne_u32_e32 vcc, 8, v128
	s_nop 1
	v_cndmask_b32_e32 v138, v233, v138, vcc
	v_cmp_ne_u32_e32 vcc, 9, v128
	s_nop 1
	v_cndmask_b32_e32 v139, v233, v139, vcc
	v_cmp_ne_u32_e32 vcc, 10, v128
	s_nop 1
	v_cndmask_b32_e32 v140, v233, v140, vcc
	v_cmp_ne_u32_e32 vcc, 11, v128
	s_nop 1
	v_cndmask_b32_e32 v141, v233, v141, vcc
	v_cmp_ne_u32_e32 vcc, 12, v128
	s_nop 1
	v_cndmask_b32_e32 v142, v233, v142, vcc
	v_cmp_ne_u32_e32 vcc, 13, v128
	s_nop 1
	v_cndmask_b32_e32 v143, v233, v143, vcc
	v_cmp_ne_u32_e32 vcc, 14, v128
	s_nop 1
	v_cndmask_b32_e32 v156, v233, v156, vcc
	v_cmp_ne_u32_e32 vcc, 15, v128
	s_nop 1
	v_cndmask_b32_e32 v157, v233, v157, vcc
	v_cmp_ne_u32_e32 vcc, 16, v128
	s_nop 1
	v_cndmask_b32_e32 v158, v233, v158, vcc
	v_cmp_ne_u32_e32 vcc, 17, v128
	s_nop 1
	v_cndmask_b32_e32 v159, v233, v159, vcc
	v_cmp_ne_u32_e32 vcc, 18, v128
	s_nop 1
	v_cndmask_b32_e32 v160, v233, v160, vcc
	v_cmp_ne_u32_e32 vcc, 19, v128
	s_nop 1
	v_cndmask_b32_e32 v161, v233, v161, vcc
	v_cmp_ne_u32_e32 vcc, 20, v128
	s_nop 1
	v_cndmask_b32_e32 v162, v233, v162, vcc
	v_cmp_ne_u32_e32 vcc, 21, v128
	s_nop 1
	v_cndmask_b32_e32 v163, v233, v163, vcc
	v_cmp_ne_u32_e32 vcc, 22, v128
	s_nop 1
	v_cndmask_b32_e32 v164, v233, v164, vcc
	v_cmp_ne_u32_e32 vcc, 23, v128
	s_nop 1
	v_cndmask_b32_e32 v165, v233, v165, vcc
	v_cmp_ne_u32_e32 vcc, 24, v128
	s_nop 1
	v_cndmask_b32_e32 v166, v233, v166, vcc
	v_cmp_ne_u32_e32 vcc, 25, v128
	s_nop 1
	v_cndmask_b32_e32 v167, v233, v167, vcc
	v_cmp_ne_u32_e32 vcc, 26, v128
	s_nop 1
	v_cndmask_b32_e32 v168, v233, v168, vcc
	v_cmp_ne_u32_e32 vcc, 27, v128
	s_nop 1
	v_cndmask_b32_e32 v169, v233, v169, vcc
	v_cmp_ne_u32_e32 vcc, 28, v128
	s_nop 1
	v_cndmask_b32_e32 v170, v233, v170, vcc
	v_cmp_ne_u32_e32 vcc, 29, v128
	s_nop 1
	v_cndmask_b32_e32 v171, v233, v171, vcc
	v_cmp_ne_u32_e32 vcc, 30, v128
	s_nop 1
	v_cndmask_b32_e32 v172, v233, v172, vcc
	v_cmp_ne_u32_e32 vcc, 31, v128
	s_nop 1
	v_cndmask_b32_e32 v173, v233, v173, vcc
	v_cmp_gt_f32_e32 vcc, v131, v129
	s_nop 1
	v_cndmask_b32_e32 v129, v129, v131, vcc
	v_cndmask_b32_e64 v175, 0, 1, vcc
	v_cmp_gt_f32_e32 vcc, v132, v129
	s_nop 1
	v_cndmask_b32_e32 v129, v129, v132, vcc
	v_cndmask_b32_e64 v175, v175, 2, vcc
	v_cmp_gt_f32_e32 vcc, v133, v129
	s_nop 1
	v_cndmask_b32_e32 v129, v129, v133, vcc
	v_cndmask_b32_e64 v175, v175, 3, vcc
	v_cmp_gt_f32_e32 vcc, v134, v129
	s_nop 1
	v_cndmask_b32_e32 v129, v129, v134, vcc
	v_cndmask_b32_e64 v175, v175, 4, vcc
	v_cmp_gt_f32_e32 vcc, v135, v129
	s_nop 1
	v_cndmask_b32_e32 v129, v129, v135, vcc
	v_cndmask_b32_e64 v175, v175, 5, vcc
	v_cmp_gt_f32_e32 vcc, v136, v129
	s_nop 1
	v_cndmask_b32_e32 v129, v129, v136, vcc
	v_cndmask_b32_e64 v175, v175, 6, vcc
	v_cmp_gt_f32_e32 vcc, v137, v129
	s_nop 1
	v_cndmask_b32_e32 v129, v129, v137, vcc
	v_cndmask_b32_e64 v175, v175, 7, vcc
	v_cmp_gt_f32_e32 vcc, v138, v129
	s_nop 1
	v_cndmask_b32_e32 v129, v129, v138, vcc
	v_cndmask_b32_e64 v175, v175, 8, vcc
	v_cmp_gt_f32_e32 vcc, v139, v129
	s_nop 1
	v_cndmask_b32_e32 v129, v129, v139, vcc
	v_cndmask_b32_e64 v175, v175, 9, vcc
	v_cmp_gt_f32_e32 vcc, v140, v129
	s_nop 1
	v_cndmask_b32_e32 v129, v129, v140, vcc
	v_cndmask_b32_e64 v175, v175, 10, vcc
	v_cmp_gt_f32_e32 vcc, v141, v129
	s_nop 1
	v_cndmask_b32_e32 v129, v129, v141, vcc
	v_cndmask_b32_e64 v175, v175, 11, vcc
	v_cmp_gt_f32_e32 vcc, v142, v129
	s_nop 1
	v_cndmask_b32_e32 v129, v129, v142, vcc
	v_cndmask_b32_e64 v175, v175, 12, vcc
	v_cmp_gt_f32_e32 vcc, v143, v129
	s_nop 1
	v_cndmask_b32_e32 v129, v129, v143, vcc
	v_cndmask_b32_e64 v175, v175, 13, vcc
	v_cmp_gt_f32_e32 vcc, v156, v129
	s_nop 1
	v_cndmask_b32_e32 v129, v129, v156, vcc
	v_cndmask_b32_e64 v175, v175, 14, vcc
	v_cmp_gt_f32_e32 vcc, v157, v129
	s_nop 1
	v_cndmask_b32_e32 v129, v129, v157, vcc
	v_cndmask_b32_e64 v175, v175, 15, vcc
	v_cmp_gt_f32_e32 vcc, v158, v129
	s_nop 1
	v_cndmask_b32_e32 v129, v129, v158, vcc
	v_cndmask_b32_e64 v175, v175, 16, vcc
	v_cmp_gt_f32_e32 vcc, v159, v129
	s_nop 1
	v_cndmask_b32_e32 v129, v129, v159, vcc
	v_cndmask_b32_e64 v175, v175, 17, vcc
	v_cmp_gt_f32_e32 vcc, v160, v129
	s_nop 1
	v_cndmask_b32_e32 v129, v129, v160, vcc
	v_cndmask_b32_e64 v175, v175, 18, vcc
	v_cmp_gt_f32_e32 vcc, v161, v129
	s_nop 1
	v_cndmask_b32_e32 v129, v129, v161, vcc
	v_cndmask_b32_e64 v175, v175, 19, vcc
	v_cmp_gt_f32_e32 vcc, v162, v129
	s_nop 1
	v_cndmask_b32_e32 v129, v129, v162, vcc
	v_cndmask_b32_e64 v175, v175, 20, vcc
	v_cmp_gt_f32_e32 vcc, v163, v129
	s_nop 1
	v_cndmask_b32_e32 v129, v129, v163, vcc
	v_cndmask_b32_e64 v175, v175, 21, vcc
	v_cmp_gt_f32_e32 vcc, v164, v129
	s_nop 1
	v_cndmask_b32_e32 v129, v129, v164, vcc
	v_cndmask_b32_e64 v175, v175, 22, vcc
	v_cmp_gt_f32_e32 vcc, v165, v129
	s_nop 1
	v_cndmask_b32_e32 v129, v129, v165, vcc
	v_cndmask_b32_e64 v175, v175, 23, vcc
	v_cmp_gt_f32_e32 vcc, v166, v129
	s_nop 1
	v_cndmask_b32_e32 v129, v129, v166, vcc
	v_cndmask_b32_e64 v175, v175, 24, vcc
	v_cmp_gt_f32_e32 vcc, v167, v129
	s_nop 1
	v_cndmask_b32_e32 v129, v129, v167, vcc
	v_cndmask_b32_e64 v175, v175, 25, vcc
	v_cmp_gt_f32_e32 vcc, v168, v129
	s_nop 1
	v_cndmask_b32_e32 v129, v129, v168, vcc
	v_cndmask_b32_e64 v175, v175, 26, vcc
	v_cmp_gt_f32_e32 vcc, v169, v129
	s_nop 1
	v_cndmask_b32_e32 v129, v129, v169, vcc
	v_cndmask_b32_e64 v175, v175, 27, vcc
	v_cmp_gt_f32_e32 vcc, v170, v129
	s_nop 1
	v_cndmask_b32_e32 v129, v129, v170, vcc
	v_cndmask_b32_e64 v175, v175, 28, vcc
	v_cmp_gt_f32_e32 vcc, v171, v129
	s_nop 1
	v_cndmask_b32_e32 v129, v129, v171, vcc
	v_cndmask_b32_e64 v175, v175, 29, vcc
	v_cmp_gt_f32_e32 vcc, v172, v129
	s_nop 1
	v_cndmask_b32_e32 v176, v129, v172, vcc
	v_cndmask_b32_e64 v175, v175, 30, vcc
	v_cmp_gt_f32_e32 vcc, v173, v176
	s_nop 1
	v_cndmask_b32_e64 v129, v175, 31, vcc
	v_cndmask_b32_e32 v175, v176, v173, vcc
	v_cmp_ne_u32_e32 vcc, 0, v129
	s_nop 1
	v_cndmask_b32_e32 v176, v233, v130, vcc
	v_cmp_ne_u32_e32 vcc, 1, v129
	v_max_f32_e32 v130, v176, v176
	v_max_f32_e32 v130, 0xff800000, v130
	v_cndmask_b32_e32 v131, v233, v131, vcc
	v_cmp_ne_u32_e32 vcc, 2, v129
	s_nop 1
	v_cndmask_b32_e32 v132, v233, v132, vcc
	v_cmp_ne_u32_e32 vcc, 3, v129
	s_nop 1
	v_cndmask_b32_e32 v133, v233, v133, vcc
	v_cmp_ne_u32_e32 vcc, 4, v129
	s_nop 1
	v_cndmask_b32_e32 v134, v233, v134, vcc
	v_cmp_ne_u32_e32 vcc, 5, v129
	s_nop 1
	v_cndmask_b32_e32 v135, v233, v135, vcc
	v_cmp_ne_u32_e32 vcc, 6, v129
	s_nop 1
	v_cndmask_b32_e32 v136, v233, v136, vcc
	v_cmp_ne_u32_e32 vcc, 7, v129
	s_nop 1
	v_cndmask_b32_e32 v137, v233, v137, vcc
	v_cmp_ne_u32_e32 vcc, 8, v129
	s_nop 1
	v_cndmask_b32_e32 v138, v233, v138, vcc
	v_cmp_ne_u32_e32 vcc, 9, v129
	s_nop 1
	v_cndmask_b32_e32 v139, v233, v139, vcc
	v_cmp_ne_u32_e32 vcc, 10, v129
	s_nop 1
	v_cndmask_b32_e32 v140, v233, v140, vcc
	v_cmp_ne_u32_e32 vcc, 11, v129
	s_nop 1
	v_cndmask_b32_e32 v141, v233, v141, vcc
	v_cmp_ne_u32_e32 vcc, 12, v129
	s_nop 1
	v_cndmask_b32_e32 v142, v233, v142, vcc
	v_cmp_ne_u32_e32 vcc, 13, v129
	s_nop 1
	v_cndmask_b32_e32 v143, v233, v143, vcc
	v_cmp_ne_u32_e32 vcc, 14, v129
	s_nop 1
	v_cndmask_b32_e32 v156, v233, v156, vcc
	v_cmp_ne_u32_e32 vcc, 15, v129
	s_nop 1
	v_cndmask_b32_e32 v157, v233, v157, vcc
	v_cmp_ne_u32_e32 vcc, 16, v129
	s_nop 1
	v_cndmask_b32_e32 v158, v233, v158, vcc
	v_cmp_ne_u32_e32 vcc, 17, v129
	s_nop 1
	v_cndmask_b32_e32 v159, v233, v159, vcc
	v_cmp_ne_u32_e32 vcc, 18, v129
	s_nop 1
	v_cndmask_b32_e32 v160, v233, v160, vcc
	v_cmp_ne_u32_e32 vcc, 19, v129
	s_nop 1
	v_cndmask_b32_e32 v161, v233, v161, vcc
	v_cmp_ne_u32_e32 vcc, 20, v129
	s_nop 1
	v_cndmask_b32_e32 v162, v233, v162, vcc
	v_cmp_ne_u32_e32 vcc, 21, v129
	s_nop 1
	v_cndmask_b32_e32 v163, v233, v163, vcc
	v_cmp_ne_u32_e32 vcc, 22, v129
	s_nop 1
	v_cndmask_b32_e32 v164, v233, v164, vcc
	v_cmp_ne_u32_e32 vcc, 23, v129
	s_nop 1
	v_cndmask_b32_e32 v165, v233, v165, vcc
	v_cmp_ne_u32_e32 vcc, 24, v129
	s_nop 1
	v_cndmask_b32_e32 v166, v233, v166, vcc
	v_cmp_ne_u32_e32 vcc, 25, v129
	s_nop 1
	v_cndmask_b32_e32 v167, v233, v167, vcc
	v_cmp_ne_u32_e32 vcc, 26, v129
	s_nop 1
	v_cndmask_b32_e32 v168, v233, v168, vcc
	v_cmp_ne_u32_e32 vcc, 27, v129
	s_nop 1
	v_cndmask_b32_e32 v169, v233, v169, vcc
	v_cmp_ne_u32_e32 vcc, 28, v129
	s_nop 1
	v_cndmask_b32_e32 v170, v233, v170, vcc
	v_cmp_ne_u32_e32 vcc, 29, v129
	s_nop 1
	v_cndmask_b32_e32 v171, v233, v171, vcc
	v_cmp_ne_u32_e32 vcc, 30, v129
	s_nop 1
	v_cndmask_b32_e32 v172, v233, v172, vcc
	v_cmp_ne_u32_e32 vcc, 31, v129
	s_nop 1
	v_cndmask_b32_e32 v173, v233, v173, vcc
	v_cmp_gt_f32_e32 vcc, v131, v130
	s_nop 1
	v_cndmask_b32_e32 v130, v130, v131, vcc
	v_cndmask_b32_e64 v177, 0, 1, vcc
	v_cmp_gt_f32_e32 vcc, v132, v130
	s_nop 1
	v_cndmask_b32_e32 v130, v130, v132, vcc
	v_cndmask_b32_e64 v177, v177, 2, vcc
	v_cmp_gt_f32_e32 vcc, v133, v130
	s_nop 1
	v_cndmask_b32_e32 v130, v130, v133, vcc
	v_cndmask_b32_e64 v177, v177, 3, vcc
	v_cmp_gt_f32_e32 vcc, v134, v130
	s_nop 1
	v_cndmask_b32_e32 v130, v130, v134, vcc
	v_cndmask_b32_e64 v177, v177, 4, vcc
	v_cmp_gt_f32_e32 vcc, v135, v130
	s_nop 1
	v_cndmask_b32_e32 v130, v130, v135, vcc
	v_cndmask_b32_e64 v177, v177, 5, vcc
	v_cmp_gt_f32_e32 vcc, v136, v130
	s_nop 1
	v_cndmask_b32_e32 v130, v130, v136, vcc
	v_cndmask_b32_e64 v177, v177, 6, vcc
	v_cmp_gt_f32_e32 vcc, v137, v130
	s_nop 1
	v_cndmask_b32_e32 v130, v130, v137, vcc
	v_cndmask_b32_e64 v177, v177, 7, vcc
	v_cmp_gt_f32_e32 vcc, v138, v130
	s_nop 1
	v_cndmask_b32_e32 v130, v130, v138, vcc
	v_cndmask_b32_e64 v177, v177, 8, vcc
	v_cmp_gt_f32_e32 vcc, v139, v130
	s_nop 1
	v_cndmask_b32_e32 v130, v130, v139, vcc
	v_cndmask_b32_e64 v177, v177, 9, vcc
	v_cmp_gt_f32_e32 vcc, v140, v130
	s_nop 1
	v_cndmask_b32_e32 v130, v130, v140, vcc
	v_cndmask_b32_e64 v177, v177, 10, vcc
	v_cmp_gt_f32_e32 vcc, v141, v130
	s_nop 1
	v_cndmask_b32_e32 v130, v130, v141, vcc
	v_cndmask_b32_e64 v177, v177, 11, vcc
	v_cmp_gt_f32_e32 vcc, v142, v130
	s_nop 1
	v_cndmask_b32_e32 v130, v130, v142, vcc
	v_cndmask_b32_e64 v177, v177, 12, vcc
	v_cmp_gt_f32_e32 vcc, v143, v130
	s_nop 1
	v_cndmask_b32_e32 v130, v130, v143, vcc
	v_cndmask_b32_e64 v177, v177, 13, vcc
	v_cmp_gt_f32_e32 vcc, v156, v130
	s_nop 1
	v_cndmask_b32_e32 v130, v130, v156, vcc
	v_cndmask_b32_e64 v177, v177, 14, vcc
	v_cmp_gt_f32_e32 vcc, v157, v130
	s_nop 1
	v_cndmask_b32_e32 v130, v130, v157, vcc
	v_cndmask_b32_e64 v177, v177, 15, vcc
	v_cmp_gt_f32_e32 vcc, v158, v130
	s_nop 1
	v_cndmask_b32_e32 v130, v130, v158, vcc
	v_cndmask_b32_e64 v177, v177, 16, vcc
	v_cmp_gt_f32_e32 vcc, v159, v130
	s_nop 1
	v_cndmask_b32_e32 v130, v130, v159, vcc
	v_cndmask_b32_e64 v177, v177, 17, vcc
	v_cmp_gt_f32_e32 vcc, v160, v130
	s_nop 1
	v_cndmask_b32_e32 v130, v130, v160, vcc
	v_cndmask_b32_e64 v177, v177, 18, vcc
	v_cmp_gt_f32_e32 vcc, v161, v130
	s_nop 1
	v_cndmask_b32_e32 v130, v130, v161, vcc
	v_cndmask_b32_e64 v177, v177, 19, vcc
	v_cmp_gt_f32_e32 vcc, v162, v130
	s_nop 1
	v_cndmask_b32_e32 v130, v130, v162, vcc
	v_cndmask_b32_e64 v177, v177, 20, vcc
	v_cmp_gt_f32_e32 vcc, v163, v130
	s_nop 1
	v_cndmask_b32_e32 v130, v130, v163, vcc
	v_cndmask_b32_e64 v177, v177, 21, vcc
	v_cmp_gt_f32_e32 vcc, v164, v130
	s_nop 1
	v_cndmask_b32_e32 v130, v130, v164, vcc
	v_cndmask_b32_e64 v177, v177, 22, vcc
	v_cmp_gt_f32_e32 vcc, v165, v130
	s_nop 1
	v_cndmask_b32_e32 v130, v130, v165, vcc
	v_cndmask_b32_e64 v177, v177, 23, vcc
	v_cmp_gt_f32_e32 vcc, v166, v130
	s_nop 1
	v_cndmask_b32_e32 v130, v130, v166, vcc
	v_cndmask_b32_e64 v177, v177, 24, vcc
	v_cmp_gt_f32_e32 vcc, v167, v130
	s_nop 1
	v_cndmask_b32_e32 v130, v130, v167, vcc
	v_cndmask_b32_e64 v177, v177, 25, vcc
	v_cmp_gt_f32_e32 vcc, v168, v130
	s_nop 1
	v_cndmask_b32_e32 v130, v130, v168, vcc
	v_cndmask_b32_e64 v177, v177, 26, vcc
	v_cmp_gt_f32_e32 vcc, v169, v130
	s_nop 1
	v_cndmask_b32_e32 v130, v130, v169, vcc
	v_cndmask_b32_e64 v177, v177, 27, vcc
	v_cmp_gt_f32_e32 vcc, v170, v130
	s_nop 1
	v_cndmask_b32_e32 v130, v130, v170, vcc
	v_cndmask_b32_e64 v177, v177, 28, vcc
	v_cmp_gt_f32_e32 vcc, v171, v130
	s_nop 1
	v_cndmask_b32_e32 v130, v130, v171, vcc
	v_cndmask_b32_e64 v177, v177, 29, vcc
	v_cmp_gt_f32_e32 vcc, v172, v130
	s_nop 1
	v_cndmask_b32_e32 v178, v130, v172, vcc
	v_cndmask_b32_e64 v177, v177, 30, vcc
	v_cmp_gt_f32_e32 vcc, v173, v178
	s_nop 1
	v_cndmask_b32_e64 v130, v177, 31, vcc
	v_cndmask_b32_e32 v177, v178, v173, vcc
	v_cmp_ne_u32_e32 vcc, 0, v130
	s_nop 1
	v_cndmask_b32_e32 v176, v233, v176, vcc
	v_cmp_ne_u32_e32 vcc, 1, v130
	v_max_f32_e32 v176, v176, v176
	v_max_f32_e32 v176, 0xff800000, v176
	v_cndmask_b32_e32 v131, v233, v131, vcc
	v_cmp_ne_u32_e32 vcc, 2, v130
	s_nop 1
	v_cndmask_b32_e32 v132, v233, v132, vcc
	v_cmp_ne_u32_e32 vcc, 3, v130
	s_nop 1
	v_cndmask_b32_e32 v133, v233, v133, vcc
	v_cmp_ne_u32_e32 vcc, 4, v130
	s_nop 1
	v_cndmask_b32_e32 v134, v233, v134, vcc
	v_cmp_ne_u32_e32 vcc, 5, v130
	s_nop 1
	v_cndmask_b32_e32 v135, v233, v135, vcc
	v_cmp_ne_u32_e32 vcc, 6, v130
	s_nop 1
	v_cndmask_b32_e32 v136, v233, v136, vcc
	v_cmp_ne_u32_e32 vcc, 7, v130
	s_nop 1
	v_cndmask_b32_e32 v137, v233, v137, vcc
	v_cmp_ne_u32_e32 vcc, 8, v130
	s_nop 1
	v_cndmask_b32_e32 v138, v233, v138, vcc
	v_cmp_ne_u32_e32 vcc, 9, v130
	s_nop 1
	v_cndmask_b32_e32 v139, v233, v139, vcc
	v_cmp_ne_u32_e32 vcc, 10, v130
	s_nop 1
	v_cndmask_b32_e32 v140, v233, v140, vcc
	v_cmp_ne_u32_e32 vcc, 11, v130
	s_nop 1
	v_cndmask_b32_e32 v141, v233, v141, vcc
	v_cmp_ne_u32_e32 vcc, 12, v130
	s_nop 1
	v_cndmask_b32_e32 v142, v233, v142, vcc
	v_cmp_ne_u32_e32 vcc, 13, v130
	s_nop 1
	v_cndmask_b32_e32 v143, v233, v143, vcc
	v_cmp_ne_u32_e32 vcc, 14, v130
	s_nop 1
	v_cndmask_b32_e32 v156, v233, v156, vcc
	v_cmp_ne_u32_e32 vcc, 15, v130
	s_nop 1
	v_cndmask_b32_e32 v157, v233, v157, vcc
	v_cmp_ne_u32_e32 vcc, 16, v130
	s_nop 1
	v_cndmask_b32_e32 v158, v233, v158, vcc
	v_cmp_ne_u32_e32 vcc, 17, v130
	s_nop 1
	v_cndmask_b32_e32 v159, v233, v159, vcc
	v_cmp_ne_u32_e32 vcc, 18, v130
	s_nop 1
	v_cndmask_b32_e32 v160, v233, v160, vcc
	v_cmp_ne_u32_e32 vcc, 19, v130
	s_nop 1
	v_cndmask_b32_e32 v161, v233, v161, vcc
	v_cmp_ne_u32_e32 vcc, 20, v130
	s_nop 1
	v_cndmask_b32_e32 v162, v233, v162, vcc
	v_cmp_ne_u32_e32 vcc, 21, v130
	s_nop 1
	v_cndmask_b32_e32 v163, v233, v163, vcc
	v_cmp_ne_u32_e32 vcc, 22, v130
	s_nop 1
	v_cndmask_b32_e32 v164, v233, v164, vcc
	v_cmp_ne_u32_e32 vcc, 23, v130
	s_nop 1
	v_cndmask_b32_e32 v165, v233, v165, vcc
	v_cmp_ne_u32_e32 vcc, 24, v130
	s_nop 1
	v_cndmask_b32_e32 v166, v233, v166, vcc
	v_cmp_ne_u32_e32 vcc, 25, v130
	s_nop 1
	v_cndmask_b32_e32 v167, v233, v167, vcc
	v_cmp_ne_u32_e32 vcc, 26, v130
	s_nop 1
	v_cndmask_b32_e32 v168, v233, v168, vcc
	v_cmp_ne_u32_e32 vcc, 27, v130
	s_nop 1
	v_cndmask_b32_e32 v169, v233, v169, vcc
	v_cmp_ne_u32_e32 vcc, 28, v130
	s_nop 1
	v_cndmask_b32_e32 v170, v233, v170, vcc
	v_cmp_ne_u32_e32 vcc, 29, v130
	s_nop 1
	v_cndmask_b32_e32 v171, v233, v171, vcc
	v_cmp_ne_u32_e32 vcc, 30, v130
	s_nop 1
	v_cndmask_b32_e32 v172, v233, v172, vcc
	v_cmp_ne_u32_e32 vcc, 31, v130
	s_nop 1
	v_cndmask_b32_e32 v173, v233, v173, vcc
	v_cmp_gt_f32_e32 vcc, v131, v176
	s_nop 1
	v_cndmask_b32_e32 v131, v176, v131, vcc
	v_cndmask_b32_e64 v178, 0, 1, vcc
	v_cmp_gt_f32_e32 vcc, v132, v131
	s_nop 1
	v_cndmask_b32_e32 v131, v131, v132, vcc
	v_cndmask_b32_e64 v176, v178, 2, vcc
	v_cmp_gt_f32_e32 vcc, v133, v131
	s_nop 1
	v_cndmask_b32_e32 v131, v131, v133, vcc
	v_cndmask_b32_e64 v132, v176, 3, vcc
	v_cmp_gt_f32_e32 vcc, v134, v131
	s_nop 1
	v_cndmask_b32_e32 v131, v131, v134, vcc
	v_cndmask_b32_e64 v132, v132, 4, vcc
	v_cmp_gt_f32_e32 vcc, v135, v131
	s_nop 1
	v_cndmask_b32_e32 v131, v131, v135, vcc
	v_cndmask_b32_e64 v132, v132, 5, vcc
	v_cmp_gt_f32_e32 vcc, v136, v131
	s_nop 1
	v_cndmask_b32_e32 v131, v131, v136, vcc
	v_cndmask_b32_e64 v132, v132, 6, vcc
	v_cmp_gt_f32_e32 vcc, v137, v131
	s_nop 1
	v_cndmask_b32_e32 v131, v131, v137, vcc
	v_cndmask_b32_e64 v132, v132, 7, vcc
	v_cmp_gt_f32_e32 vcc, v138, v131
	s_nop 1
	v_cndmask_b32_e32 v131, v131, v138, vcc
	v_cndmask_b32_e64 v132, v132, 8, vcc
	v_cmp_gt_f32_e32 vcc, v139, v131
	s_nop 1
	v_cndmask_b32_e32 v131, v131, v139, vcc
	v_cndmask_b32_e64 v132, v132, 9, vcc
	v_cmp_gt_f32_e32 vcc, v140, v131
	s_nop 1
	v_cndmask_b32_e32 v131, v131, v140, vcc
	v_cndmask_b32_e64 v132, v132, 10, vcc
	v_cmp_gt_f32_e32 vcc, v141, v131
	s_nop 1
	v_cndmask_b32_e32 v131, v131, v141, vcc
	v_cndmask_b32_e64 v132, v132, 11, vcc
	v_cmp_gt_f32_e32 vcc, v142, v131
	s_nop 1
	v_cndmask_b32_e32 v131, v131, v142, vcc
	v_cndmask_b32_e64 v132, v132, 12, vcc
	v_cmp_gt_f32_e32 vcc, v143, v131
	s_nop 1
	v_cndmask_b32_e32 v131, v131, v143, vcc
	v_cndmask_b32_e64 v132, v132, 13, vcc
	v_cmp_gt_f32_e32 vcc, v156, v131
	s_nop 1
	v_cndmask_b32_e32 v131, v131, v156, vcc
	v_cndmask_b32_e64 v132, v132, 14, vcc
	v_cmp_gt_f32_e32 vcc, v157, v131
	s_nop 1
	v_cndmask_b32_e32 v131, v131, v157, vcc
	v_cndmask_b32_e64 v132, v132, 15, vcc
	v_cmp_gt_f32_e32 vcc, v158, v131
	s_nop 1
	v_cndmask_b32_e32 v131, v131, v158, vcc
	v_cndmask_b32_e64 v132, v132, 16, vcc
	v_cmp_gt_f32_e32 vcc, v159, v131
	s_nop 1
	v_cndmask_b32_e32 v131, v131, v159, vcc
	v_cndmask_b32_e64 v132, v132, 17, vcc
	v_cmp_gt_f32_e32 vcc, v160, v131
	s_nop 1
	v_cndmask_b32_e32 v131, v131, v160, vcc
	v_cndmask_b32_e64 v132, v132, 18, vcc
	v_cmp_gt_f32_e32 vcc, v161, v131
	s_nop 1
	v_cndmask_b32_e32 v131, v131, v161, vcc
	v_cndmask_b32_e64 v132, v132, 19, vcc
	v_cmp_gt_f32_e32 vcc, v162, v131
	s_nop 1
	v_cndmask_b32_e32 v131, v131, v162, vcc
	v_cndmask_b32_e64 v132, v132, 20, vcc
	v_cmp_gt_f32_e32 vcc, v163, v131
	s_nop 1
	v_cndmask_b32_e32 v131, v131, v163, vcc
	v_cndmask_b32_e64 v132, v132, 21, vcc
	v_cmp_gt_f32_e32 vcc, v164, v131
	s_nop 1
	v_cndmask_b32_e32 v131, v131, v164, vcc
	v_cndmask_b32_e64 v132, v132, 22, vcc
	v_cmp_gt_f32_e32 vcc, v165, v131
	s_nop 1
	v_cndmask_b32_e32 v131, v131, v165, vcc
	v_cndmask_b32_e64 v132, v132, 23, vcc
	v_cmp_gt_f32_e32 vcc, v166, v131
	s_nop 1
	v_cndmask_b32_e32 v131, v131, v166, vcc
	v_cndmask_b32_e64 v132, v132, 24, vcc
	v_cmp_gt_f32_e32 vcc, v167, v131
	s_nop 1
	v_cndmask_b32_e32 v131, v131, v167, vcc
	v_cndmask_b32_e64 v132, v132, 25, vcc
	v_cmp_gt_f32_e32 vcc, v168, v131
	s_nop 1
	v_cndmask_b32_e32 v131, v131, v168, vcc
	v_cndmask_b32_e64 v132, v132, 26, vcc
	v_cmp_gt_f32_e32 vcc, v169, v131
	s_nop 1
	v_cndmask_b32_e32 v131, v131, v169, vcc
	v_cndmask_b32_e64 v132, v132, 27, vcc
	v_cmp_gt_f32_e32 vcc, v170, v131
	s_nop 1
	v_cndmask_b32_e32 v131, v131, v170, vcc
	v_cndmask_b32_e64 v132, v132, 28, vcc
	v_cmp_gt_f32_e32 vcc, v171, v131
	s_nop 1
	v_cndmask_b32_e32 v131, v131, v171, vcc
	v_cndmask_b32_e64 v132, v132, 29, vcc
	v_cmp_gt_f32_e32 vcc, v172, v131
	s_nop 1
	v_cndmask_b32_e32 v133, v131, v172, vcc
	v_cndmask_b32_e64 v132, v132, 30, vcc
	v_cmp_gt_f32_e32 vcc, v173, v133
	s_nop 1
	v_cndmask_b32_e64 v131, v132, 31, vcc
	v_cndmask_b32_e32 v132, v133, v173, vcc
	v_sub_f32_e32 v133, v175, v174
	v_mul_f32_e32 v133, 0x3fb8aa3b, v133
	v_exp_f32_e32 v134, v133
	v_sub_f32_e32 v133, v177, v174
	v_mul_f32_e32 v133, 0x3fb8aa3b, v133
	v_sub_f32_e32 v132, v132, v174
	v_exp_f32_e32 v135, v133
	v_mul_f32_e32 v132, 0x3fb8aa3b, v132
	v_exp_f32_e32 v133, v132
	v_add_f32_e32 v132, 1.0, v134
	v_add_f32_e32 v132, v132, v135
	ds_write_b128 v150, v[128:131] offset:34304
	v_add_f32_e32 v132, v132, v133
	v_div_scale_f32 v136, s[22:23], v132, v132, 1.0
	v_rcp_f32_e32 v137, v136
	s_nop 0
	v_fma_f32 v138, -v136, v137, 1.0
	v_fmac_f32_e32 v137, v138, v137
	v_div_scale_f32 v138, vcc, 1.0, v132, 1.0
	v_mul_f32_e32 v139, v138, v137
	v_fma_f32 v140, -v136, v139, v138
	v_fmac_f32_e32 v139, v140, v137
	v_fma_f32 v136, -v136, v139, v138
	v_div_fmas_f32 v136, v136, v137, v139
	v_div_fixup_f32 v132, v136, v132, 1.0
	v_pk_mul_f32 v[128:129], v[134:135], v[132:133] op_sel_hi:[1,0]
	v_mul_f32_e32 v135, v133, v132
	v_mov_b32_e32 v133, v128
	v_mov_b32_e32 v134, v129
	ds_write_b128 v150, v[132:135] offset:36352
